# A17: A13 with the light-step tail reordered (first a-update before the other-row move, y add after it)
# speedup vs baseline: 1.0041x; 1.0041x over previous
.Lrw_scan_loop:
	s_and_b32 s2, s8, 1
	s_mul_i32 s3, s2, 0xe000
	s_lshl_b32 s2, s2, 12
	v_add_u32_e32 v195, s3, v103
	v_add_u32_e32 v33, s3, v38
	v_add_u32_e32 v196, s3, v75
	v_add_u32_e32 v36, s3, v37
	v_add_u32_e32 v102, s2, v76
	ds_read_b128 v[140:143], v195 offset:0
	ds_read_b128 v[152:155], v195 offset:8192
	ds_read_b128 v[176:179], v195 offset:16384
	ds_read_b128 v[84:87], v195 offset:32768
	ds_read_b64 v[4:5], v196 offset:0
	ds_read_b32 v6, v36 offset:0
	ds_read_b128 v[144:147], v195 offset:256
	ds_read_b128 v[156:159], v195 offset:8448
	ds_read_b128 v[180:183], v195 offset:16640
	ds_read_b128 v[88:91], v195 offset:33024
	ds_read_b64 v[8:9], v196 offset:512
	ds_read_b32 v10, v36 offset:512
	s_waitcnt lgkmcnt(6)
	v_pk_mul_f32 v[46:47], v[24:25], v[140:141] op_sel_hi:[0,1]
	v_pk_mul_f32 v[34:35], v[20:21], v[140:141] op_sel_hi:[0,1]
	v_pk_fma_f32 v[46:47], v[24:25], v[142:143], v[46:47] op_sel:[1,0,0] op_sel_hi:[1,1,1]
	v_pk_fma_f32 v[34:35], v[20:21], v[142:143], v[34:35] op_sel:[1,0,0] op_sel_hi:[1,1,1]
	v_pk_fma_f32 v[46:47], v[26:27], v[152:153], v[46:47] op_sel_hi:[0,1,1]
	v_pk_fma_f32 v[34:35], v[22:23], v[152:153], v[34:35] op_sel_hi:[0,1,1]
	v_pk_fma_f32 v[46:47], v[26:27], v[154:155], v[46:47] op_sel:[1,0,0] op_sel_hi:[1,1,1]
	v_pk_fma_f32 v[34:35], v[22:23], v[154:155], v[34:35] op_sel:[1,0,0] op_sel_hi:[1,1,1]
	v_pk_fma_f32 v[20:21], v[176:177], v[4:5], v[20:21] op_sel_hi:[1,0,1]
	v_add_f32_dpp v28, v46, v34 row_half_mirror row_mask:0xf bank_mask:0xf
	v_add_f32_dpp v32, v47, v35 row_half_mirror row_mask:0xf bank_mask:0xf
	v_pk_fma_f32 v[22:23], v[178:179], v[4:5], v[22:23] op_sel_hi:[1,0,1]
	v_add_f32_dpp v28, v28, v28 row_ror:8 row_mask:0xf bank_mask:0xf
	v_add_f32_dpp v32, v32, v32 row_ror:8 row_mask:0xf bank_mask:0xf
	v_pk_fma_f32 v[24:25], v[176:177], v[6:7], v[24:25] op_sel_hi:[1,0,1]
	v_add_f32_dpp v28, v28, v28 quad_perm:[1,0,3,2] row_mask:0xf bank_mask:0xf
	v_add_f32_dpp v32, v32, v32 quad_perm:[1,0,3,2] row_mask:0xf bank_mask:0xf
	v_pk_fma_f32 v[26:27], v[178:179], v[6:7], v[26:27] op_sel_hi:[1,0,1]
	v_add_f32_dpp v28, v28, v28 quad_perm:[2,3,0,1] row_mask:0xf bank_mask:0xf
	v_add_f32_dpp v32, v32, v32 quad_perm:[2,3,0,1] row_mask:0xf bank_mask:0xf
	v_pk_fma_f32 v[20:21], v[84:85], v[28:29], v[20:21] op_sel_hi:[1,0,1] neg_lo:[0,1,0] neg_hi:[0,1,0]
	v_mov_b32_dpp v30, v28 row_half_mirror row_mask:0xf bank_mask:0xf
	v_pk_fma_f32 v[22:23], v[86:87], v[28:29], v[22:23] op_sel_hi:[1,0,1] neg_lo:[0,1,0] neg_hi:[0,1,0]
	v_add_f32_e32 v39, v32, v5
	v_pk_fma_f32 v[24:25], v[84:85], v[30:31], v[24:25] op_sel_hi:[1,0,1] neg_lo:[0,1,0] neg_hi:[0,1,0]
	v_pk_fma_f32 v[26:27], v[86:87], v[30:31], v[26:27] op_sel_hi:[1,0,1] neg_lo:[0,1,0] neg_hi:[0,1,0]
	ds_write_b32 v102, v39 offset:0
	ds_read_b128 v[140:143], v195 offset:512
	ds_read_b128 v[152:155], v195 offset:8704
	ds_read_b128 v[176:179], v195 offset:16896
	ds_read_b128 v[84:87], v195 offset:33280
	ds_read_b64 v[4:5], v196 offset:1024
	ds_read_b32 v6, v36 offset:1024
	s_waitcnt lgkmcnt(7)
	v_pk_mul_f32 v[46:47], v[24:25], v[144:145] op_sel_hi:[0,1]
	v_pk_mul_f32 v[34:35], v[20:21], v[144:145] op_sel_hi:[0,1]
	v_pk_fma_f32 v[46:47], v[24:25], v[146:147], v[46:47] op_sel:[1,0,0] op_sel_hi:[1,1,1]
	v_pk_fma_f32 v[34:35], v[20:21], v[146:147], v[34:35] op_sel:[1,0,0] op_sel_hi:[1,1,1]
	v_pk_fma_f32 v[46:47], v[26:27], v[156:157], v[46:47] op_sel_hi:[0,1,1]
	v_pk_fma_f32 v[34:35], v[22:23], v[156:157], v[34:35] op_sel_hi:[0,1,1]
	v_pk_fma_f32 v[46:47], v[26:27], v[158:159], v[46:47] op_sel:[1,0,0] op_sel_hi:[1,1,1]
	v_pk_fma_f32 v[34:35], v[22:23], v[158:159], v[34:35] op_sel:[1,0,0] op_sel_hi:[1,1,1]
	v_pk_fma_f32 v[20:21], v[180:181], v[8:9], v[20:21] op_sel_hi:[1,0,1]
	v_add_f32_dpp v28, v46, v34 row_half_mirror row_mask:0xf bank_mask:0xf
	v_add_f32_dpp v32, v47, v35 row_half_mirror row_mask:0xf bank_mask:0xf
	v_pk_fma_f32 v[22:23], v[182:183], v[8:9], v[22:23] op_sel_hi:[1,0,1]
	v_add_f32_dpp v28, v28, v28 row_ror:8 row_mask:0xf bank_mask:0xf
	v_add_f32_dpp v32, v32, v32 row_ror:8 row_mask:0xf bank_mask:0xf
	v_pk_fma_f32 v[24:25], v[180:181], v[10:11], v[24:25] op_sel_hi:[1,0,1]
	v_add_f32_dpp v28, v28, v28 quad_perm:[1,0,3,2] row_mask:0xf bank_mask:0xf
	v_add_f32_dpp v32, v32, v32 quad_perm:[1,0,3,2] row_mask:0xf bank_mask:0xf
	v_pk_fma_f32 v[26:27], v[182:183], v[10:11], v[26:27] op_sel_hi:[1,0,1]
	v_add_f32_dpp v28, v28, v28 quad_perm:[2,3,0,1] row_mask:0xf bank_mask:0xf
	v_add_f32_dpp v32, v32, v32 quad_perm:[2,3,0,1] row_mask:0xf bank_mask:0xf
	v_pk_fma_f32 v[20:21], v[88:89], v[28:29], v[20:21] op_sel_hi:[1,0,1] neg_lo:[0,1,0] neg_hi:[0,1,0]
	v_mov_b32_dpp v30, v28 row_half_mirror row_mask:0xf bank_mask:0xf
	v_pk_fma_f32 v[22:23], v[90:91], v[28:29], v[22:23] op_sel_hi:[1,0,1] neg_lo:[0,1,0] neg_hi:[0,1,0]
	v_add_f32_e32 v39, v32, v9
	v_pk_fma_f32 v[24:25], v[88:89], v[30:31], v[24:25] op_sel_hi:[1,0,1] neg_lo:[0,1,0] neg_hi:[0,1,0]
	v_pk_fma_f32 v[26:27], v[90:91], v[30:31], v[26:27] op_sel_hi:[1,0,1] neg_lo:[0,1,0] neg_hi:[0,1,0]
	ds_write_b32 v102, v39 offset:128
	ds_read_b128 v[144:147], v195 offset:768
	ds_read_b128 v[156:159], v195 offset:8960
	ds_read_b128 v[168:171], v195 offset:25344
	ds_read_b128 v[180:183], v195 offset:17152
	ds_read_b128 v[88:91], v195 offset:33536
	ds_read_b64 v[8:9], v196 offset:1536
	ds_read_b32 v10, v36 offset:1536
	s_waitcnt lgkmcnt(8)
	v_pk_mul_f32 v[46:47], v[24:25], v[140:141] op_sel_hi:[0,1]
	v_pk_mul_f32 v[34:35], v[20:21], v[140:141] op_sel_hi:[0,1]
	v_pk_fma_f32 v[46:47], v[24:25], v[142:143], v[46:47] op_sel:[1,0,0] op_sel_hi:[1,1,1]
	v_pk_fma_f32 v[34:35], v[20:21], v[142:143], v[34:35] op_sel:[1,0,0] op_sel_hi:[1,1,1]
	v_pk_fma_f32 v[46:47], v[26:27], v[152:153], v[46:47] op_sel_hi:[0,1,1]
	v_pk_fma_f32 v[34:35], v[22:23], v[152:153], v[34:35] op_sel_hi:[0,1,1]
	v_pk_fma_f32 v[46:47], v[26:27], v[154:155], v[46:47] op_sel:[1,0,0] op_sel_hi:[1,1,1]
	v_pk_fma_f32 v[34:35], v[22:23], v[154:155], v[34:35] op_sel:[1,0,0] op_sel_hi:[1,1,1]
	v_pk_fma_f32 v[20:21], v[176:177], v[4:5], v[20:21] op_sel_hi:[1,0,1]
	v_add_f32_dpp v28, v46, v34 row_half_mirror row_mask:0xf bank_mask:0xf
	v_add_f32_dpp v32, v47, v35 row_half_mirror row_mask:0xf bank_mask:0xf
	v_pk_fma_f32 v[22:23], v[178:179], v[4:5], v[22:23] op_sel_hi:[1,0,1]
	v_add_f32_dpp v28, v28, v28 row_ror:8 row_mask:0xf bank_mask:0xf
	v_add_f32_dpp v32, v32, v32 row_ror:8 row_mask:0xf bank_mask:0xf
	v_pk_fma_f32 v[24:25], v[176:177], v[6:7], v[24:25] op_sel_hi:[1,0,1]
	v_add_f32_dpp v28, v28, v28 quad_perm:[1,0,3,2] row_mask:0xf bank_mask:0xf
	v_add_f32_dpp v32, v32, v32 quad_perm:[1,0,3,2] row_mask:0xf bank_mask:0xf
	v_pk_fma_f32 v[26:27], v[178:179], v[6:7], v[26:27] op_sel_hi:[1,0,1]
	v_add_f32_dpp v28, v28, v28 quad_perm:[2,3,0,1] row_mask:0xf bank_mask:0xf
	v_add_f32_dpp v32, v32, v32 quad_perm:[2,3,0,1] row_mask:0xf bank_mask:0xf
	v_pk_fma_f32 v[20:21], v[84:85], v[28:29], v[20:21] op_sel_hi:[1,0,1] neg_lo:[0,1,0] neg_hi:[0,1,0]
	v_mov_b32_dpp v30, v28 row_half_mirror row_mask:0xf bank_mask:0xf
	v_pk_fma_f32 v[22:23], v[86:87], v[28:29], v[22:23] op_sel_hi:[1,0,1] neg_lo:[0,1,0] neg_hi:[0,1,0]
	v_add_f32_e32 v39, v32, v5
	v_pk_fma_f32 v[24:25], v[84:85], v[30:31], v[24:25] op_sel_hi:[1,0,1] neg_lo:[0,1,0] neg_hi:[0,1,0]
	v_pk_fma_f32 v[26:27], v[86:87], v[30:31], v[26:27] op_sel_hi:[1,0,1] neg_lo:[0,1,0] neg_hi:[0,1,0]
	ds_write_b32 v102, v39 offset:256
	ds_read_b128 v[140:143], v195 offset:1024
	ds_read_b128 v[152:155], v195 offset:9216
	ds_read_b128 v[176:179], v195 offset:17408
	ds_read_b128 v[84:87], v195 offset:33792
	ds_read_b64 v[4:5], v196 offset:2048
	ds_read_b32 v6, v36 offset:2048
	s_waitcnt lgkmcnt(7)
	v_pk_mul_f32 v[46:47], v[24:25], v[144:145] op_sel_hi:[0,1]
	v_pk_mul_f32 v[34:35], v[20:21], v[144:145] op_sel_hi:[0,1]
	v_pk_fma_f32 v[46:47], v[24:25], v[146:147], v[46:47] op_sel:[1,0,0] op_sel_hi:[1,1,1]
	v_pk_fma_f32 v[34:35], v[20:21], v[146:147], v[34:35] op_sel:[1,0,0] op_sel_hi:[1,1,1]
	v_pk_fma_f32 v[46:47], v[26:27], v[156:157], v[46:47] op_sel_hi:[0,1,1]
	v_pk_fma_f32 v[34:35], v[22:23], v[156:157], v[34:35] op_sel_hi:[0,1,1]
	v_pk_fma_f32 v[46:47], v[26:27], v[158:159], v[46:47] op_sel:[1,0,0] op_sel_hi:[1,1,1]
	v_pk_fma_f32 v[34:35], v[22:23], v[158:159], v[34:35] op_sel:[1,0,0] op_sel_hi:[1,1,1]
	v_pk_mul_f32 v[20:21], v[20:21], v[168:169]
	v_add_f32_dpp v28, v46, v34 row_half_mirror row_mask:0xf bank_mask:0xf
	v_add_f32_dpp v32, v47, v35 row_half_mirror row_mask:0xf bank_mask:0xf
	v_pk_mul_f32 v[22:23], v[22:23], v[170:171]
	v_add_f32_dpp v28, v28, v28 row_ror:8 row_mask:0xf bank_mask:0xf
	v_add_f32_dpp v32, v32, v32 row_ror:8 row_mask:0xf bank_mask:0xf
	v_pk_mul_f32 v[24:25], v[24:25], v[168:169]
	v_add_f32_dpp v28, v28, v28 quad_perm:[1,0,3,2] row_mask:0xf bank_mask:0xf
	v_add_f32_dpp v32, v32, v32 quad_perm:[1,0,3,2] row_mask:0xf bank_mask:0xf
	v_pk_mul_f32 v[26:27], v[26:27], v[170:171]
	v_add_f32_dpp v28, v28, v28 quad_perm:[2,3,0,1] row_mask:0xf bank_mask:0xf
	v_add_f32_dpp v32, v32, v32 quad_perm:[2,3,0,1] row_mask:0xf bank_mask:0xf
	v_pk_fma_f32 v[20:21], v[180:181], v[8:9], v[20:21] op_sel_hi:[1,0,1]
	v_mov_b32_dpp v30, v28 row_half_mirror row_mask:0xf bank_mask:0xf
	v_pk_fma_f32 v[22:23], v[182:183], v[8:9], v[22:23] op_sel_hi:[1,0,1]
	v_pk_fma_f32 v[24:25], v[180:181], v[10:11], v[24:25] op_sel_hi:[1,0,1]
	v_pk_fma_f32 v[26:27], v[182:183], v[10:11], v[26:27] op_sel_hi:[1,0,1]
	v_pk_fma_f32 v[20:21], v[88:89], v[28:29], v[20:21] op_sel_hi:[1,0,1] neg_lo:[0,1,0] neg_hi:[0,1,0]
	v_pk_fma_f32 v[22:23], v[90:91], v[28:29], v[22:23] op_sel_hi:[1,0,1] neg_lo:[0,1,0] neg_hi:[0,1,0]
	v_pk_fma_f32 v[24:25], v[88:89], v[30:31], v[24:25] op_sel_hi:[1,0,1] neg_lo:[0,1,0] neg_hi:[0,1,0]
	v_pk_fma_f32 v[26:27], v[90:91], v[30:31], v[26:27] op_sel_hi:[1,0,1] neg_lo:[0,1,0] neg_hi:[0,1,0]
	v_add_f32_e32 v39, v32, v9
	ds_write_b32 v102, v39 offset:384
	ds_read_b128 v[144:147], v195 offset:1280
	ds_read_b128 v[156:159], v195 offset:9472
	ds_read_b128 v[180:183], v195 offset:17664
	ds_read_b128 v[88:91], v195 offset:34048
	ds_read_b64 v[8:9], v196 offset:2560
	ds_read_b32 v10, v36 offset:2560
	s_waitcnt lgkmcnt(7)
	v_pk_mul_f32 v[46:47], v[24:25], v[140:141] op_sel_hi:[0,1]
	v_pk_mul_f32 v[34:35], v[20:21], v[140:141] op_sel_hi:[0,1]
	v_pk_fma_f32 v[46:47], v[24:25], v[142:143], v[46:47] op_sel:[1,0,0] op_sel_hi:[1,1,1]
	v_pk_fma_f32 v[34:35], v[20:21], v[142:143], v[34:35] op_sel:[1,0,0] op_sel_hi:[1,1,1]
	v_pk_fma_f32 v[46:47], v[26:27], v[152:153], v[46:47] op_sel_hi:[0,1,1]
	v_pk_fma_f32 v[34:35], v[22:23], v[152:153], v[34:35] op_sel_hi:[0,1,1]
	v_pk_fma_f32 v[46:47], v[26:27], v[154:155], v[46:47] op_sel:[1,0,0] op_sel_hi:[1,1,1]
	v_pk_fma_f32 v[34:35], v[22:23], v[154:155], v[34:35] op_sel:[1,0,0] op_sel_hi:[1,1,1]
	v_pk_fma_f32 v[20:21], v[176:177], v[4:5], v[20:21] op_sel_hi:[1,0,1]
	v_add_f32_dpp v28, v46, v34 row_half_mirror row_mask:0xf bank_mask:0xf
	v_add_f32_dpp v32, v47, v35 row_half_mirror row_mask:0xf bank_mask:0xf
	v_pk_fma_f32 v[22:23], v[178:179], v[4:5], v[22:23] op_sel_hi:[1,0,1]
	v_add_f32_dpp v28, v28, v28 row_ror:8 row_mask:0xf bank_mask:0xf
	v_add_f32_dpp v32, v32, v32 row_ror:8 row_mask:0xf bank_mask:0xf
	v_pk_fma_f32 v[24:25], v[176:177], v[6:7], v[24:25] op_sel_hi:[1,0,1]
	v_add_f32_dpp v28, v28, v28 quad_perm:[1,0,3,2] row_mask:0xf bank_mask:0xf
	v_add_f32_dpp v32, v32, v32 quad_perm:[1,0,3,2] row_mask:0xf bank_mask:0xf
	v_pk_fma_f32 v[26:27], v[178:179], v[6:7], v[26:27] op_sel_hi:[1,0,1]
	v_add_f32_dpp v28, v28, v28 quad_perm:[2,3,0,1] row_mask:0xf bank_mask:0xf
	v_add_f32_dpp v32, v32, v32 quad_perm:[2,3,0,1] row_mask:0xf bank_mask:0xf
	v_pk_fma_f32 v[20:21], v[84:85], v[28:29], v[20:21] op_sel_hi:[1,0,1] neg_lo:[0,1,0] neg_hi:[0,1,0]
	v_mov_b32_dpp v30, v28 row_half_mirror row_mask:0xf bank_mask:0xf
	v_pk_fma_f32 v[22:23], v[86:87], v[28:29], v[22:23] op_sel_hi:[1,0,1] neg_lo:[0,1,0] neg_hi:[0,1,0]
	v_add_f32_e32 v39, v32, v5
	v_pk_fma_f32 v[24:25], v[84:85], v[30:31], v[24:25] op_sel_hi:[1,0,1] neg_lo:[0,1,0] neg_hi:[0,1,0]
	v_pk_fma_f32 v[26:27], v[86:87], v[30:31], v[26:27] op_sel_hi:[1,0,1] neg_lo:[0,1,0] neg_hi:[0,1,0]
	ds_write_b32 v102, v39 offset:512
	ds_read_b128 v[140:143], v195 offset:1536
	ds_read_b128 v[152:155], v195 offset:9728
	ds_read_b128 v[176:179], v195 offset:17920
	ds_read_b128 v[84:87], v195 offset:34304
	ds_read_b64 v[4:5], v196 offset:3072
	ds_read_b32 v6, v36 offset:3072
	s_waitcnt lgkmcnt(7)
	v_pk_mul_f32 v[46:47], v[24:25], v[144:145] op_sel_hi:[0,1]
	v_pk_mul_f32 v[34:35], v[20:21], v[144:145] op_sel_hi:[0,1]
	v_pk_fma_f32 v[46:47], v[24:25], v[146:147], v[46:47] op_sel:[1,0,0] op_sel_hi:[1,1,1]
	v_pk_fma_f32 v[34:35], v[20:21], v[146:147], v[34:35] op_sel:[1,0,0] op_sel_hi:[1,1,1]
	v_pk_fma_f32 v[46:47], v[26:27], v[156:157], v[46:47] op_sel_hi:[0,1,1]
	v_pk_fma_f32 v[34:35], v[22:23], v[156:157], v[34:35] op_sel_hi:[0,1,1]
	v_pk_fma_f32 v[46:47], v[26:27], v[158:159], v[46:47] op_sel:[1,0,0] op_sel_hi:[1,1,1]
	v_pk_fma_f32 v[34:35], v[22:23], v[158:159], v[34:35] op_sel:[1,0,0] op_sel_hi:[1,1,1]
	v_pk_fma_f32 v[20:21], v[180:181], v[8:9], v[20:21] op_sel_hi:[1,0,1]
	v_add_f32_dpp v28, v46, v34 row_half_mirror row_mask:0xf bank_mask:0xf
	v_add_f32_dpp v32, v47, v35 row_half_mirror row_mask:0xf bank_mask:0xf
	v_pk_fma_f32 v[22:23], v[182:183], v[8:9], v[22:23] op_sel_hi:[1,0,1]
	v_add_f32_dpp v28, v28, v28 row_ror:8 row_mask:0xf bank_mask:0xf
	v_add_f32_dpp v32, v32, v32 row_ror:8 row_mask:0xf bank_mask:0xf
	v_pk_fma_f32 v[24:25], v[180:181], v[10:11], v[24:25] op_sel_hi:[1,0,1]
	v_add_f32_dpp v28, v28, v28 quad_perm:[1,0,3,2] row_mask:0xf bank_mask:0xf
	v_add_f32_dpp v32, v32, v32 quad_perm:[1,0,3,2] row_mask:0xf bank_mask:0xf
	v_pk_fma_f32 v[26:27], v[182:183], v[10:11], v[26:27] op_sel_hi:[1,0,1]
	v_add_f32_dpp v28, v28, v28 quad_perm:[2,3,0,1] row_mask:0xf bank_mask:0xf
	v_add_f32_dpp v32, v32, v32 quad_perm:[2,3,0,1] row_mask:0xf bank_mask:0xf
	v_pk_fma_f32 v[20:21], v[88:89], v[28:29], v[20:21] op_sel_hi:[1,0,1] neg_lo:[0,1,0] neg_hi:[0,1,0]
	v_mov_b32_dpp v30, v28 row_half_mirror row_mask:0xf bank_mask:0xf
	v_pk_fma_f32 v[22:23], v[90:91], v[28:29], v[22:23] op_sel_hi:[1,0,1] neg_lo:[0,1,0] neg_hi:[0,1,0]
	v_add_f32_e32 v39, v32, v9
	v_pk_fma_f32 v[24:25], v[88:89], v[30:31], v[24:25] op_sel_hi:[1,0,1] neg_lo:[0,1,0] neg_hi:[0,1,0]
	v_pk_fma_f32 v[26:27], v[90:91], v[30:31], v[26:27] op_sel_hi:[1,0,1] neg_lo:[0,1,0] neg_hi:[0,1,0]
	ds_write_b32 v102, v39 offset:640
	ds_read_b128 v[144:147], v195 offset:1792
	ds_read_b128 v[156:159], v195 offset:9984
	ds_read_b128 v[168:171], v195 offset:26368
	ds_read_b128 v[180:183], v195 offset:18176
	ds_read_b128 v[88:91], v195 offset:34560
	ds_read_b64 v[8:9], v196 offset:3584
	ds_read_b32 v10, v36 offset:3584
	s_waitcnt lgkmcnt(8)
	v_pk_mul_f32 v[46:47], v[24:25], v[140:141] op_sel_hi:[0,1]
	v_pk_mul_f32 v[34:35], v[20:21], v[140:141] op_sel_hi:[0,1]
	v_pk_fma_f32 v[46:47], v[24:25], v[142:143], v[46:47] op_sel:[1,0,0] op_sel_hi:[1,1,1]
	v_pk_fma_f32 v[34:35], v[20:21], v[142:143], v[34:35] op_sel:[1,0,0] op_sel_hi:[1,1,1]
	v_pk_fma_f32 v[46:47], v[26:27], v[152:153], v[46:47] op_sel_hi:[0,1,1]
	v_pk_fma_f32 v[34:35], v[22:23], v[152:153], v[34:35] op_sel_hi:[0,1,1]
	v_pk_fma_f32 v[46:47], v[26:27], v[154:155], v[46:47] op_sel:[1,0,0] op_sel_hi:[1,1,1]
	v_pk_fma_f32 v[34:35], v[22:23], v[154:155], v[34:35] op_sel:[1,0,0] op_sel_hi:[1,1,1]
	v_pk_fma_f32 v[20:21], v[176:177], v[4:5], v[20:21] op_sel_hi:[1,0,1]
	v_add_f32_dpp v28, v46, v34 row_half_mirror row_mask:0xf bank_mask:0xf
	v_add_f32_dpp v32, v47, v35 row_half_mirror row_mask:0xf bank_mask:0xf
	v_pk_fma_f32 v[22:23], v[178:179], v[4:5], v[22:23] op_sel_hi:[1,0,1]
	v_add_f32_dpp v28, v28, v28 row_ror:8 row_mask:0xf bank_mask:0xf
	v_add_f32_dpp v32, v32, v32 row_ror:8 row_mask:0xf bank_mask:0xf
	v_pk_fma_f32 v[24:25], v[176:177], v[6:7], v[24:25] op_sel_hi:[1,0,1]
	v_add_f32_dpp v28, v28, v28 quad_perm:[1,0,3,2] row_mask:0xf bank_mask:0xf
	v_add_f32_dpp v32, v32, v32 quad_perm:[1,0,3,2] row_mask:0xf bank_mask:0xf
	v_pk_fma_f32 v[26:27], v[178:179], v[6:7], v[26:27] op_sel_hi:[1,0,1]
	v_add_f32_dpp v28, v28, v28 quad_perm:[2,3,0,1] row_mask:0xf bank_mask:0xf
	v_add_f32_dpp v32, v32, v32 quad_perm:[2,3,0,1] row_mask:0xf bank_mask:0xf
	v_pk_fma_f32 v[20:21], v[84:85], v[28:29], v[20:21] op_sel_hi:[1,0,1] neg_lo:[0,1,0] neg_hi:[0,1,0]
	v_mov_b32_dpp v30, v28 row_half_mirror row_mask:0xf bank_mask:0xf
	v_pk_fma_f32 v[22:23], v[86:87], v[28:29], v[22:23] op_sel_hi:[1,0,1] neg_lo:[0,1,0] neg_hi:[0,1,0]
	v_add_f32_e32 v39, v32, v5
	v_pk_fma_f32 v[24:25], v[84:85], v[30:31], v[24:25] op_sel_hi:[1,0,1] neg_lo:[0,1,0] neg_hi:[0,1,0]
	v_pk_fma_f32 v[26:27], v[86:87], v[30:31], v[26:27] op_sel_hi:[1,0,1] neg_lo:[0,1,0] neg_hi:[0,1,0]
	ds_write_b32 v102, v39 offset:768
	ds_read_b128 v[140:143], v195 offset:2048
	ds_read_b128 v[152:155], v195 offset:10240
	ds_read_b128 v[176:179], v195 offset:18432
	ds_read_b128 v[84:87], v195 offset:34816
	ds_read_b64 v[4:5], v196 offset:4096
	ds_read_b32 v6, v36 offset:4096
	s_waitcnt lgkmcnt(7)
	v_pk_mul_f32 v[46:47], v[24:25], v[144:145] op_sel_hi:[0,1]
	v_pk_mul_f32 v[34:35], v[20:21], v[144:145] op_sel_hi:[0,1]
	v_pk_fma_f32 v[46:47], v[24:25], v[146:147], v[46:47] op_sel:[1,0,0] op_sel_hi:[1,1,1]
	v_pk_fma_f32 v[34:35], v[20:21], v[146:147], v[34:35] op_sel:[1,0,0] op_sel_hi:[1,1,1]
	v_pk_fma_f32 v[46:47], v[26:27], v[156:157], v[46:47] op_sel_hi:[0,1,1]
	v_pk_fma_f32 v[34:35], v[22:23], v[156:157], v[34:35] op_sel_hi:[0,1,1]
	v_pk_fma_f32 v[46:47], v[26:27], v[158:159], v[46:47] op_sel:[1,0,0] op_sel_hi:[1,1,1]
	v_pk_fma_f32 v[34:35], v[22:23], v[158:159], v[34:35] op_sel:[1,0,0] op_sel_hi:[1,1,1]
	v_pk_mul_f32 v[20:21], v[20:21], v[168:169]
	v_add_f32_dpp v28, v46, v34 row_half_mirror row_mask:0xf bank_mask:0xf
	v_add_f32_dpp v32, v47, v35 row_half_mirror row_mask:0xf bank_mask:0xf
	v_pk_mul_f32 v[22:23], v[22:23], v[170:171]
	v_add_f32_dpp v28, v28, v28 row_ror:8 row_mask:0xf bank_mask:0xf
	v_add_f32_dpp v32, v32, v32 row_ror:8 row_mask:0xf bank_mask:0xf
	v_pk_mul_f32 v[24:25], v[24:25], v[168:169]
	v_add_f32_dpp v28, v28, v28 quad_perm:[1,0,3,2] row_mask:0xf bank_mask:0xf
	v_add_f32_dpp v32, v32, v32 quad_perm:[1,0,3,2] row_mask:0xf bank_mask:0xf
	v_pk_mul_f32 v[26:27], v[26:27], v[170:171]
	v_add_f32_dpp v28, v28, v28 quad_perm:[2,3,0,1] row_mask:0xf bank_mask:0xf
	v_add_f32_dpp v32, v32, v32 quad_perm:[2,3,0,1] row_mask:0xf bank_mask:0xf
	v_pk_fma_f32 v[20:21], v[180:181], v[8:9], v[20:21] op_sel_hi:[1,0,1]
	v_mov_b32_dpp v30, v28 row_half_mirror row_mask:0xf bank_mask:0xf
	v_pk_fma_f32 v[22:23], v[182:183], v[8:9], v[22:23] op_sel_hi:[1,0,1]
	v_pk_fma_f32 v[24:25], v[180:181], v[10:11], v[24:25] op_sel_hi:[1,0,1]
	v_pk_fma_f32 v[26:27], v[182:183], v[10:11], v[26:27] op_sel_hi:[1,0,1]
	v_pk_fma_f32 v[20:21], v[88:89], v[28:29], v[20:21] op_sel_hi:[1,0,1] neg_lo:[0,1,0] neg_hi:[0,1,0]
	v_pk_fma_f32 v[22:23], v[90:91], v[28:29], v[22:23] op_sel_hi:[1,0,1] neg_lo:[0,1,0] neg_hi:[0,1,0]
	v_pk_fma_f32 v[24:25], v[88:89], v[30:31], v[24:25] op_sel_hi:[1,0,1] neg_lo:[0,1,0] neg_hi:[0,1,0]
	v_pk_fma_f32 v[26:27], v[90:91], v[30:31], v[26:27] op_sel_hi:[1,0,1] neg_lo:[0,1,0] neg_hi:[0,1,0]
	v_add_f32_e32 v39, v32, v9
	ds_write_b32 v102, v39 offset:896
	ds_read_b128 v[144:147], v195 offset:2304
	ds_read_b128 v[156:159], v195 offset:10496
	ds_read_b128 v[180:183], v195 offset:18688
	ds_read_b128 v[88:91], v195 offset:35072
	ds_read_b64 v[8:9], v196 offset:4608
	ds_read_b32 v10, v36 offset:4608
	s_waitcnt lgkmcnt(7)
	v_pk_mul_f32 v[46:47], v[24:25], v[140:141] op_sel_hi:[0,1]
	v_pk_mul_f32 v[34:35], v[20:21], v[140:141] op_sel_hi:[0,1]
	v_pk_fma_f32 v[46:47], v[24:25], v[142:143], v[46:47] op_sel:[1,0,0] op_sel_hi:[1,1,1]
	v_pk_fma_f32 v[34:35], v[20:21], v[142:143], v[34:35] op_sel:[1,0,0] op_sel_hi:[1,1,1]
	v_pk_fma_f32 v[46:47], v[26:27], v[152:153], v[46:47] op_sel_hi:[0,1,1]
	v_pk_fma_f32 v[34:35], v[22:23], v[152:153], v[34:35] op_sel_hi:[0,1,1]
	v_pk_fma_f32 v[46:47], v[26:27], v[154:155], v[46:47] op_sel:[1,0,0] op_sel_hi:[1,1,1]
	v_pk_fma_f32 v[34:35], v[22:23], v[154:155], v[34:35] op_sel:[1,0,0] op_sel_hi:[1,1,1]
	v_pk_fma_f32 v[20:21], v[176:177], v[4:5], v[20:21] op_sel_hi:[1,0,1]
	v_add_f32_dpp v28, v46, v34 row_half_mirror row_mask:0xf bank_mask:0xf
	v_add_f32_dpp v32, v47, v35 row_half_mirror row_mask:0xf bank_mask:0xf
	v_pk_fma_f32 v[22:23], v[178:179], v[4:5], v[22:23] op_sel_hi:[1,0,1]
	v_add_f32_dpp v28, v28, v28 row_ror:8 row_mask:0xf bank_mask:0xf
	v_add_f32_dpp v32, v32, v32 row_ror:8 row_mask:0xf bank_mask:0xf
	v_pk_fma_f32 v[24:25], v[176:177], v[6:7], v[24:25] op_sel_hi:[1,0,1]
	v_add_f32_dpp v28, v28, v28 quad_perm:[1,0,3,2] row_mask:0xf bank_mask:0xf
	v_add_f32_dpp v32, v32, v32 quad_perm:[1,0,3,2] row_mask:0xf bank_mask:0xf
	v_pk_fma_f32 v[26:27], v[178:179], v[6:7], v[26:27] op_sel_hi:[1,0,1]
	v_add_f32_dpp v28, v28, v28 quad_perm:[2,3,0,1] row_mask:0xf bank_mask:0xf
	v_add_f32_dpp v32, v32, v32 quad_perm:[2,3,0,1] row_mask:0xf bank_mask:0xf
	v_pk_fma_f32 v[20:21], v[84:85], v[28:29], v[20:21] op_sel_hi:[1,0,1] neg_lo:[0,1,0] neg_hi:[0,1,0]
	v_mov_b32_dpp v30, v28 row_half_mirror row_mask:0xf bank_mask:0xf
	v_pk_fma_f32 v[22:23], v[86:87], v[28:29], v[22:23] op_sel_hi:[1,0,1] neg_lo:[0,1,0] neg_hi:[0,1,0]
	v_add_f32_e32 v39, v32, v5
	v_pk_fma_f32 v[24:25], v[84:85], v[30:31], v[24:25] op_sel_hi:[1,0,1] neg_lo:[0,1,0] neg_hi:[0,1,0]
	v_pk_fma_f32 v[26:27], v[86:87], v[30:31], v[26:27] op_sel_hi:[1,0,1] neg_lo:[0,1,0] neg_hi:[0,1,0]
	ds_write_b32 v102, v39 offset:1024
	ds_read_b128 v[140:143], v195 offset:2560
	ds_read_b128 v[152:155], v195 offset:10752
	ds_read_b128 v[176:179], v195 offset:18944
	ds_read_b128 v[84:87], v195 offset:35328
	ds_read_b64 v[4:5], v196 offset:5120
	ds_read_b32 v6, v36 offset:5120
	s_waitcnt lgkmcnt(7)
	v_pk_mul_f32 v[46:47], v[24:25], v[144:145] op_sel_hi:[0,1]
	v_pk_mul_f32 v[34:35], v[20:21], v[144:145] op_sel_hi:[0,1]
	v_pk_fma_f32 v[46:47], v[24:25], v[146:147], v[46:47] op_sel:[1,0,0] op_sel_hi:[1,1,1]
	v_pk_fma_f32 v[34:35], v[20:21], v[146:147], v[34:35] op_sel:[1,0,0] op_sel_hi:[1,1,1]
	v_pk_fma_f32 v[46:47], v[26:27], v[156:157], v[46:47] op_sel_hi:[0,1,1]
	v_pk_fma_f32 v[34:35], v[22:23], v[156:157], v[34:35] op_sel_hi:[0,1,1]
	v_pk_fma_f32 v[46:47], v[26:27], v[158:159], v[46:47] op_sel:[1,0,0] op_sel_hi:[1,1,1]
	v_pk_fma_f32 v[34:35], v[22:23], v[158:159], v[34:35] op_sel:[1,0,0] op_sel_hi:[1,1,1]
	v_pk_fma_f32 v[20:21], v[180:181], v[8:9], v[20:21] op_sel_hi:[1,0,1]
	v_add_f32_dpp v28, v46, v34 row_half_mirror row_mask:0xf bank_mask:0xf
	v_add_f32_dpp v32, v47, v35 row_half_mirror row_mask:0xf bank_mask:0xf
	v_pk_fma_f32 v[22:23], v[182:183], v[8:9], v[22:23] op_sel_hi:[1,0,1]
	v_add_f32_dpp v28, v28, v28 row_ror:8 row_mask:0xf bank_mask:0xf
	v_add_f32_dpp v32, v32, v32 row_ror:8 row_mask:0xf bank_mask:0xf
	v_pk_fma_f32 v[24:25], v[180:181], v[10:11], v[24:25] op_sel_hi:[1,0,1]
	v_add_f32_dpp v28, v28, v28 quad_perm:[1,0,3,2] row_mask:0xf bank_mask:0xf
	v_add_f32_dpp v32, v32, v32 quad_perm:[1,0,3,2] row_mask:0xf bank_mask:0xf
	v_pk_fma_f32 v[26:27], v[182:183], v[10:11], v[26:27] op_sel_hi:[1,0,1]
	v_add_f32_dpp v28, v28, v28 quad_perm:[2,3,0,1] row_mask:0xf bank_mask:0xf
	v_add_f32_dpp v32, v32, v32 quad_perm:[2,3,0,1] row_mask:0xf bank_mask:0xf
	v_pk_fma_f32 v[20:21], v[88:89], v[28:29], v[20:21] op_sel_hi:[1,0,1] neg_lo:[0,1,0] neg_hi:[0,1,0]
	v_mov_b32_dpp v30, v28 row_half_mirror row_mask:0xf bank_mask:0xf
	v_pk_fma_f32 v[22:23], v[90:91], v[28:29], v[22:23] op_sel_hi:[1,0,1] neg_lo:[0,1,0] neg_hi:[0,1,0]
	v_add_f32_e32 v39, v32, v9
	v_pk_fma_f32 v[24:25], v[88:89], v[30:31], v[24:25] op_sel_hi:[1,0,1] neg_lo:[0,1,0] neg_hi:[0,1,0]
	v_pk_fma_f32 v[26:27], v[90:91], v[30:31], v[26:27] op_sel_hi:[1,0,1] neg_lo:[0,1,0] neg_hi:[0,1,0]
	ds_write_b32 v102, v39 offset:1152
	ds_read_b128 v[144:147], v195 offset:2816
	ds_read_b128 v[156:159], v195 offset:11008
	ds_read_b128 v[168:171], v195 offset:27392
	ds_read_b128 v[180:183], v195 offset:19200
	ds_read_b128 v[88:91], v195 offset:35584
	ds_read_b64 v[8:9], v196 offset:5632
	ds_read_b32 v10, v36 offset:5632
	s_waitcnt lgkmcnt(8)
	v_pk_mul_f32 v[46:47], v[24:25], v[140:141] op_sel_hi:[0,1]
	v_pk_mul_f32 v[34:35], v[20:21], v[140:141] op_sel_hi:[0,1]
	v_pk_fma_f32 v[46:47], v[24:25], v[142:143], v[46:47] op_sel:[1,0,0] op_sel_hi:[1,1,1]
	v_pk_fma_f32 v[34:35], v[20:21], v[142:143], v[34:35] op_sel:[1,0,0] op_sel_hi:[1,1,1]
	v_pk_fma_f32 v[46:47], v[26:27], v[152:153], v[46:47] op_sel_hi:[0,1,1]
	v_pk_fma_f32 v[34:35], v[22:23], v[152:153], v[34:35] op_sel_hi:[0,1,1]
	v_pk_fma_f32 v[46:47], v[26:27], v[154:155], v[46:47] op_sel:[1,0,0] op_sel_hi:[1,1,1]
	v_pk_fma_f32 v[34:35], v[22:23], v[154:155], v[34:35] op_sel:[1,0,0] op_sel_hi:[1,1,1]
	v_pk_fma_f32 v[20:21], v[176:177], v[4:5], v[20:21] op_sel_hi:[1,0,1]
	v_add_f32_dpp v28, v46, v34 row_half_mirror row_mask:0xf bank_mask:0xf
	v_add_f32_dpp v32, v47, v35 row_half_mirror row_mask:0xf bank_mask:0xf
	v_pk_fma_f32 v[22:23], v[178:179], v[4:5], v[22:23] op_sel_hi:[1,0,1]
	v_add_f32_dpp v28, v28, v28 row_ror:8 row_mask:0xf bank_mask:0xf
	v_add_f32_dpp v32, v32, v32 row_ror:8 row_mask:0xf bank_mask:0xf
	v_pk_fma_f32 v[24:25], v[176:177], v[6:7], v[24:25] op_sel_hi:[1,0,1]
	v_add_f32_dpp v28, v28, v28 quad_perm:[1,0,3,2] row_mask:0xf bank_mask:0xf
	v_add_f32_dpp v32, v32, v32 quad_perm:[1,0,3,2] row_mask:0xf bank_mask:0xf
	v_pk_fma_f32 v[26:27], v[178:179], v[6:7], v[26:27] op_sel_hi:[1,0,1]
	v_add_f32_dpp v28, v28, v28 quad_perm:[2,3,0,1] row_mask:0xf bank_mask:0xf
	v_add_f32_dpp v32, v32, v32 quad_perm:[2,3,0,1] row_mask:0xf bank_mask:0xf
	v_pk_fma_f32 v[20:21], v[84:85], v[28:29], v[20:21] op_sel_hi:[1,0,1] neg_lo:[0,1,0] neg_hi:[0,1,0]
	v_mov_b32_dpp v30, v28 row_half_mirror row_mask:0xf bank_mask:0xf
	v_pk_fma_f32 v[22:23], v[86:87], v[28:29], v[22:23] op_sel_hi:[1,0,1] neg_lo:[0,1,0] neg_hi:[0,1,0]
	v_add_f32_e32 v39, v32, v5
	v_pk_fma_f32 v[24:25], v[84:85], v[30:31], v[24:25] op_sel_hi:[1,0,1] neg_lo:[0,1,0] neg_hi:[0,1,0]
	v_pk_fma_f32 v[26:27], v[86:87], v[30:31], v[26:27] op_sel_hi:[1,0,1] neg_lo:[0,1,0] neg_hi:[0,1,0]
	ds_write_b32 v102, v39 offset:1280
	ds_read_b128 v[140:143], v195 offset:3072
	ds_read_b128 v[152:155], v195 offset:11264
	ds_read_b128 v[176:179], v195 offset:19456
	ds_read_b128 v[84:87], v195 offset:35840
	ds_read_b64 v[4:5], v196 offset:6144
	ds_read_b32 v6, v36 offset:6144
	s_waitcnt lgkmcnt(7)
	v_pk_mul_f32 v[46:47], v[24:25], v[144:145] op_sel_hi:[0,1]
	v_pk_mul_f32 v[34:35], v[20:21], v[144:145] op_sel_hi:[0,1]
	v_pk_fma_f32 v[46:47], v[24:25], v[146:147], v[46:47] op_sel:[1,0,0] op_sel_hi:[1,1,1]
	v_pk_fma_f32 v[34:35], v[20:21], v[146:147], v[34:35] op_sel:[1,0,0] op_sel_hi:[1,1,1]
	v_pk_fma_f32 v[46:47], v[26:27], v[156:157], v[46:47] op_sel_hi:[0,1,1]
	v_pk_fma_f32 v[34:35], v[22:23], v[156:157], v[34:35] op_sel_hi:[0,1,1]
	v_pk_fma_f32 v[46:47], v[26:27], v[158:159], v[46:47] op_sel:[1,0,0] op_sel_hi:[1,1,1]
	v_pk_fma_f32 v[34:35], v[22:23], v[158:159], v[34:35] op_sel:[1,0,0] op_sel_hi:[1,1,1]
	v_pk_mul_f32 v[20:21], v[20:21], v[168:169]
	v_add_f32_dpp v28, v46, v34 row_half_mirror row_mask:0xf bank_mask:0xf
	v_add_f32_dpp v32, v47, v35 row_half_mirror row_mask:0xf bank_mask:0xf
	v_pk_mul_f32 v[22:23], v[22:23], v[170:171]
	v_add_f32_dpp v28, v28, v28 row_ror:8 row_mask:0xf bank_mask:0xf
	v_add_f32_dpp v32, v32, v32 row_ror:8 row_mask:0xf bank_mask:0xf
	v_pk_mul_f32 v[24:25], v[24:25], v[168:169]
	v_add_f32_dpp v28, v28, v28 quad_perm:[1,0,3,2] row_mask:0xf bank_mask:0xf
	v_add_f32_dpp v32, v32, v32 quad_perm:[1,0,3,2] row_mask:0xf bank_mask:0xf
	v_pk_mul_f32 v[26:27], v[26:27], v[170:171]
	v_add_f32_dpp v28, v28, v28 quad_perm:[2,3,0,1] row_mask:0xf bank_mask:0xf
	v_add_f32_dpp v32, v32, v32 quad_perm:[2,3,0,1] row_mask:0xf bank_mask:0xf
	v_pk_fma_f32 v[20:21], v[180:181], v[8:9], v[20:21] op_sel_hi:[1,0,1]
	v_mov_b32_dpp v30, v28 row_half_mirror row_mask:0xf bank_mask:0xf
	v_pk_fma_f32 v[22:23], v[182:183], v[8:9], v[22:23] op_sel_hi:[1,0,1]
	v_pk_fma_f32 v[24:25], v[180:181], v[10:11], v[24:25] op_sel_hi:[1,0,1]
	v_pk_fma_f32 v[26:27], v[182:183], v[10:11], v[26:27] op_sel_hi:[1,0,1]
	v_pk_fma_f32 v[20:21], v[88:89], v[28:29], v[20:21] op_sel_hi:[1,0,1] neg_lo:[0,1,0] neg_hi:[0,1,0]
	v_pk_fma_f32 v[22:23], v[90:91], v[28:29], v[22:23] op_sel_hi:[1,0,1] neg_lo:[0,1,0] neg_hi:[0,1,0]
	v_pk_fma_f32 v[24:25], v[88:89], v[30:31], v[24:25] op_sel_hi:[1,0,1] neg_lo:[0,1,0] neg_hi:[0,1,0]
	v_pk_fma_f32 v[26:27], v[90:91], v[30:31], v[26:27] op_sel_hi:[1,0,1] neg_lo:[0,1,0] neg_hi:[0,1,0]
	v_add_f32_e32 v39, v32, v9
	ds_write_b32 v102, v39 offset:1408
	ds_read_b128 v[144:147], v195 offset:3328
	ds_read_b128 v[156:159], v195 offset:11520
	ds_read_b128 v[180:183], v195 offset:19712
	ds_read_b128 v[88:91], v195 offset:36096
	ds_read_b64 v[8:9], v196 offset:6656
	ds_read_b32 v10, v36 offset:6656
	s_waitcnt lgkmcnt(7)
	v_pk_mul_f32 v[46:47], v[24:25], v[140:141] op_sel_hi:[0,1]
	v_pk_mul_f32 v[34:35], v[20:21], v[140:141] op_sel_hi:[0,1]
	v_pk_fma_f32 v[46:47], v[24:25], v[142:143], v[46:47] op_sel:[1,0,0] op_sel_hi:[1,1,1]
	v_pk_fma_f32 v[34:35], v[20:21], v[142:143], v[34:35] op_sel:[1,0,0] op_sel_hi:[1,1,1]
	v_pk_fma_f32 v[46:47], v[26:27], v[152:153], v[46:47] op_sel_hi:[0,1,1]
	v_pk_fma_f32 v[34:35], v[22:23], v[152:153], v[34:35] op_sel_hi:[0,1,1]
	v_pk_fma_f32 v[46:47], v[26:27], v[154:155], v[46:47] op_sel:[1,0,0] op_sel_hi:[1,1,1]
	v_pk_fma_f32 v[34:35], v[22:23], v[154:155], v[34:35] op_sel:[1,0,0] op_sel_hi:[1,1,1]
	v_pk_fma_f32 v[20:21], v[176:177], v[4:5], v[20:21] op_sel_hi:[1,0,1]
	v_add_f32_dpp v28, v46, v34 row_half_mirror row_mask:0xf bank_mask:0xf
	v_add_f32_dpp v32, v47, v35 row_half_mirror row_mask:0xf bank_mask:0xf
	v_pk_fma_f32 v[22:23], v[178:179], v[4:5], v[22:23] op_sel_hi:[1,0,1]
	v_add_f32_dpp v28, v28, v28 row_ror:8 row_mask:0xf bank_mask:0xf
	v_add_f32_dpp v32, v32, v32 row_ror:8 row_mask:0xf bank_mask:0xf
	v_pk_fma_f32 v[24:25], v[176:177], v[6:7], v[24:25] op_sel_hi:[1,0,1]
	v_add_f32_dpp v28, v28, v28 quad_perm:[1,0,3,2] row_mask:0xf bank_mask:0xf
	v_add_f32_dpp v32, v32, v32 quad_perm:[1,0,3,2] row_mask:0xf bank_mask:0xf
	v_pk_fma_f32 v[26:27], v[178:179], v[6:7], v[26:27] op_sel_hi:[1,0,1]
	v_add_f32_dpp v28, v28, v28 quad_perm:[2,3,0,1] row_mask:0xf bank_mask:0xf
	v_add_f32_dpp v32, v32, v32 quad_perm:[2,3,0,1] row_mask:0xf bank_mask:0xf
	v_pk_fma_f32 v[20:21], v[84:85], v[28:29], v[20:21] op_sel_hi:[1,0,1] neg_lo:[0,1,0] neg_hi:[0,1,0]
	v_mov_b32_dpp v30, v28 row_half_mirror row_mask:0xf bank_mask:0xf
	v_pk_fma_f32 v[22:23], v[86:87], v[28:29], v[22:23] op_sel_hi:[1,0,1] neg_lo:[0,1,0] neg_hi:[0,1,0]
	v_add_f32_e32 v39, v32, v5
	v_pk_fma_f32 v[24:25], v[84:85], v[30:31], v[24:25] op_sel_hi:[1,0,1] neg_lo:[0,1,0] neg_hi:[0,1,0]
	v_pk_fma_f32 v[26:27], v[86:87], v[30:31], v[26:27] op_sel_hi:[1,0,1] neg_lo:[0,1,0] neg_hi:[0,1,0]
	ds_write_b32 v102, v39 offset:1536
	ds_read_b128 v[140:143], v195 offset:3584
	ds_read_b128 v[152:155], v195 offset:11776
	ds_read_b128 v[176:179], v195 offset:19968
	ds_read_b128 v[84:87], v195 offset:36352
	ds_read_b64 v[4:5], v196 offset:7168
	ds_read_b32 v6, v36 offset:7168
	s_waitcnt lgkmcnt(7)
	v_pk_mul_f32 v[46:47], v[24:25], v[144:145] op_sel_hi:[0,1]
	v_pk_mul_f32 v[34:35], v[20:21], v[144:145] op_sel_hi:[0,1]
	v_pk_fma_f32 v[46:47], v[24:25], v[146:147], v[46:47] op_sel:[1,0,0] op_sel_hi:[1,1,1]
	v_pk_fma_f32 v[34:35], v[20:21], v[146:147], v[34:35] op_sel:[1,0,0] op_sel_hi:[1,1,1]
	v_pk_fma_f32 v[46:47], v[26:27], v[156:157], v[46:47] op_sel_hi:[0,1,1]
	v_pk_fma_f32 v[34:35], v[22:23], v[156:157], v[34:35] op_sel_hi:[0,1,1]
	v_pk_fma_f32 v[46:47], v[26:27], v[158:159], v[46:47] op_sel:[1,0,0] op_sel_hi:[1,1,1]
	v_pk_fma_f32 v[34:35], v[22:23], v[158:159], v[34:35] op_sel:[1,0,0] op_sel_hi:[1,1,1]
	v_pk_fma_f32 v[20:21], v[180:181], v[8:9], v[20:21] op_sel_hi:[1,0,1]
	v_add_f32_dpp v28, v46, v34 row_half_mirror row_mask:0xf bank_mask:0xf
	v_add_f32_dpp v32, v47, v35 row_half_mirror row_mask:0xf bank_mask:0xf
	v_pk_fma_f32 v[22:23], v[182:183], v[8:9], v[22:23] op_sel_hi:[1,0,1]
	v_add_f32_dpp v28, v28, v28 row_ror:8 row_mask:0xf bank_mask:0xf
	v_add_f32_dpp v32, v32, v32 row_ror:8 row_mask:0xf bank_mask:0xf
	v_pk_fma_f32 v[24:25], v[180:181], v[10:11], v[24:25] op_sel_hi:[1,0,1]
	v_add_f32_dpp v28, v28, v28 quad_perm:[1,0,3,2] row_mask:0xf bank_mask:0xf
	v_add_f32_dpp v32, v32, v32 quad_perm:[1,0,3,2] row_mask:0xf bank_mask:0xf
	v_pk_fma_f32 v[26:27], v[182:183], v[10:11], v[26:27] op_sel_hi:[1,0,1]
	v_add_f32_dpp v28, v28, v28 quad_perm:[2,3,0,1] row_mask:0xf bank_mask:0xf
	v_add_f32_dpp v32, v32, v32 quad_perm:[2,3,0,1] row_mask:0xf bank_mask:0xf
	v_pk_fma_f32 v[20:21], v[88:89], v[28:29], v[20:21] op_sel_hi:[1,0,1] neg_lo:[0,1,0] neg_hi:[0,1,0]
	v_mov_b32_dpp v30, v28 row_half_mirror row_mask:0xf bank_mask:0xf
	v_pk_fma_f32 v[22:23], v[90:91], v[28:29], v[22:23] op_sel_hi:[1,0,1] neg_lo:[0,1,0] neg_hi:[0,1,0]
	v_add_f32_e32 v39, v32, v9
	v_pk_fma_f32 v[24:25], v[88:89], v[30:31], v[24:25] op_sel_hi:[1,0,1] neg_lo:[0,1,0] neg_hi:[0,1,0]
	v_pk_fma_f32 v[26:27], v[90:91], v[30:31], v[26:27] op_sel_hi:[1,0,1] neg_lo:[0,1,0] neg_hi:[0,1,0]
	ds_write_b32 v102, v39 offset:1664
	ds_read_b128 v[144:147], v195 offset:3840
	ds_read_b128 v[156:159], v195 offset:12032
	ds_read_b128 v[168:171], v195 offset:28416
	ds_read_b128 v[180:183], v195 offset:20224
	ds_read_b128 v[88:91], v195 offset:36608
	ds_read_b64 v[8:9], v196 offset:7680
	ds_read_b32 v10, v36 offset:7680
	s_waitcnt lgkmcnt(8)
	v_pk_mul_f32 v[46:47], v[24:25], v[140:141] op_sel_hi:[0,1]
	v_pk_mul_f32 v[34:35], v[20:21], v[140:141] op_sel_hi:[0,1]
	v_pk_fma_f32 v[46:47], v[24:25], v[142:143], v[46:47] op_sel:[1,0,0] op_sel_hi:[1,1,1]
	v_pk_fma_f32 v[34:35], v[20:21], v[142:143], v[34:35] op_sel:[1,0,0] op_sel_hi:[1,1,1]
	v_pk_fma_f32 v[46:47], v[26:27], v[152:153], v[46:47] op_sel_hi:[0,1,1]
	v_pk_fma_f32 v[34:35], v[22:23], v[152:153], v[34:35] op_sel_hi:[0,1,1]
	v_pk_fma_f32 v[46:47], v[26:27], v[154:155], v[46:47] op_sel:[1,0,0] op_sel_hi:[1,1,1]
	v_pk_fma_f32 v[34:35], v[22:23], v[154:155], v[34:35] op_sel:[1,0,0] op_sel_hi:[1,1,1]
	v_pk_fma_f32 v[20:21], v[176:177], v[4:5], v[20:21] op_sel_hi:[1,0,1]
	v_add_f32_dpp v28, v46, v34 row_half_mirror row_mask:0xf bank_mask:0xf
	v_add_f32_dpp v32, v47, v35 row_half_mirror row_mask:0xf bank_mask:0xf
	v_pk_fma_f32 v[22:23], v[178:179], v[4:5], v[22:23] op_sel_hi:[1,0,1]
	v_add_f32_dpp v28, v28, v28 row_ror:8 row_mask:0xf bank_mask:0xf
	v_add_f32_dpp v32, v32, v32 row_ror:8 row_mask:0xf bank_mask:0xf
	v_pk_fma_f32 v[24:25], v[176:177], v[6:7], v[24:25] op_sel_hi:[1,0,1]
	v_add_f32_dpp v28, v28, v28 quad_perm:[1,0,3,2] row_mask:0xf bank_mask:0xf
	v_add_f32_dpp v32, v32, v32 quad_perm:[1,0,3,2] row_mask:0xf bank_mask:0xf
	v_pk_fma_f32 v[26:27], v[178:179], v[6:7], v[26:27] op_sel_hi:[1,0,1]
	v_add_f32_dpp v28, v28, v28 quad_perm:[2,3,0,1] row_mask:0xf bank_mask:0xf
	v_add_f32_dpp v32, v32, v32 quad_perm:[2,3,0,1] row_mask:0xf bank_mask:0xf
	v_pk_fma_f32 v[20:21], v[84:85], v[28:29], v[20:21] op_sel_hi:[1,0,1] neg_lo:[0,1,0] neg_hi:[0,1,0]
	v_mov_b32_dpp v30, v28 row_half_mirror row_mask:0xf bank_mask:0xf
	v_pk_fma_f32 v[22:23], v[86:87], v[28:29], v[22:23] op_sel_hi:[1,0,1] neg_lo:[0,1,0] neg_hi:[0,1,0]
	v_add_f32_e32 v39, v32, v5
	v_pk_fma_f32 v[24:25], v[84:85], v[30:31], v[24:25] op_sel_hi:[1,0,1] neg_lo:[0,1,0] neg_hi:[0,1,0]
	v_pk_fma_f32 v[26:27], v[86:87], v[30:31], v[26:27] op_sel_hi:[1,0,1] neg_lo:[0,1,0] neg_hi:[0,1,0]
	ds_write_b32 v102, v39 offset:1792
	ds_read_b128 v[140:143], v195 offset:4096
	ds_read_b128 v[152:155], v195 offset:12288
	ds_read_b128 v[176:179], v195 offset:20480
	ds_read_b128 v[84:87], v195 offset:36864
	ds_read_b64 v[4:5], v196 offset:8192
	ds_read_b32 v6, v36 offset:8192
	s_waitcnt lgkmcnt(7)
	v_pk_mul_f32 v[46:47], v[24:25], v[144:145] op_sel_hi:[0,1]
	v_pk_mul_f32 v[34:35], v[20:21], v[144:145] op_sel_hi:[0,1]
	v_pk_fma_f32 v[46:47], v[24:25], v[146:147], v[46:47] op_sel:[1,0,0] op_sel_hi:[1,1,1]
	v_pk_fma_f32 v[34:35], v[20:21], v[146:147], v[34:35] op_sel:[1,0,0] op_sel_hi:[1,1,1]
	v_pk_fma_f32 v[46:47], v[26:27], v[156:157], v[46:47] op_sel_hi:[0,1,1]
	v_pk_fma_f32 v[34:35], v[22:23], v[156:157], v[34:35] op_sel_hi:[0,1,1]
	v_pk_fma_f32 v[46:47], v[26:27], v[158:159], v[46:47] op_sel:[1,0,0] op_sel_hi:[1,1,1]
	v_pk_fma_f32 v[34:35], v[22:23], v[158:159], v[34:35] op_sel:[1,0,0] op_sel_hi:[1,1,1]
	v_pk_mul_f32 v[20:21], v[20:21], v[168:169]
	v_add_f32_dpp v28, v46, v34 row_half_mirror row_mask:0xf bank_mask:0xf
	v_add_f32_dpp v32, v47, v35 row_half_mirror row_mask:0xf bank_mask:0xf
	v_pk_mul_f32 v[22:23], v[22:23], v[170:171]
	v_add_f32_dpp v28, v28, v28 row_ror:8 row_mask:0xf bank_mask:0xf
	v_add_f32_dpp v32, v32, v32 row_ror:8 row_mask:0xf bank_mask:0xf
	v_pk_mul_f32 v[24:25], v[24:25], v[168:169]
	v_add_f32_dpp v28, v28, v28 quad_perm:[1,0,3,2] row_mask:0xf bank_mask:0xf
	v_add_f32_dpp v32, v32, v32 quad_perm:[1,0,3,2] row_mask:0xf bank_mask:0xf
	v_pk_mul_f32 v[26:27], v[26:27], v[170:171]
	v_add_f32_dpp v28, v28, v28 quad_perm:[2,3,0,1] row_mask:0xf bank_mask:0xf
	v_add_f32_dpp v32, v32, v32 quad_perm:[2,3,0,1] row_mask:0xf bank_mask:0xf
	v_pk_fma_f32 v[20:21], v[180:181], v[8:9], v[20:21] op_sel_hi:[1,0,1]
	v_mov_b32_dpp v30, v28 row_half_mirror row_mask:0xf bank_mask:0xf
	v_pk_fma_f32 v[22:23], v[182:183], v[8:9], v[22:23] op_sel_hi:[1,0,1]
	v_pk_fma_f32 v[24:25], v[180:181], v[10:11], v[24:25] op_sel_hi:[1,0,1]
	v_pk_fma_f32 v[26:27], v[182:183], v[10:11], v[26:27] op_sel_hi:[1,0,1]
	v_pk_fma_f32 v[20:21], v[88:89], v[28:29], v[20:21] op_sel_hi:[1,0,1] neg_lo:[0,1,0] neg_hi:[0,1,0]
	v_pk_fma_f32 v[22:23], v[90:91], v[28:29], v[22:23] op_sel_hi:[1,0,1] neg_lo:[0,1,0] neg_hi:[0,1,0]
	v_pk_fma_f32 v[24:25], v[88:89], v[30:31], v[24:25] op_sel_hi:[1,0,1] neg_lo:[0,1,0] neg_hi:[0,1,0]
	v_pk_fma_f32 v[26:27], v[90:91], v[30:31], v[26:27] op_sel_hi:[1,0,1] neg_lo:[0,1,0] neg_hi:[0,1,0]
	v_add_f32_e32 v39, v32, v9
	ds_write_b32 v102, v39 offset:1920
	ds_read_b128 v[144:147], v195 offset:4352
	ds_read_b128 v[156:159], v195 offset:12544
	ds_read_b128 v[180:183], v195 offset:20736
	ds_read_b128 v[88:91], v195 offset:37120
	ds_read_b64 v[8:9], v196 offset:8704
	ds_read_b32 v10, v36 offset:8704
	s_waitcnt lgkmcnt(7)
	v_pk_mul_f32 v[46:47], v[24:25], v[140:141] op_sel_hi:[0,1]
	v_pk_mul_f32 v[34:35], v[20:21], v[140:141] op_sel_hi:[0,1]
	v_pk_fma_f32 v[46:47], v[24:25], v[142:143], v[46:47] op_sel:[1,0,0] op_sel_hi:[1,1,1]
	v_pk_fma_f32 v[34:35], v[20:21], v[142:143], v[34:35] op_sel:[1,0,0] op_sel_hi:[1,1,1]
	v_pk_fma_f32 v[46:47], v[26:27], v[152:153], v[46:47] op_sel_hi:[0,1,1]
	v_pk_fma_f32 v[34:35], v[22:23], v[152:153], v[34:35] op_sel_hi:[0,1,1]
	v_pk_fma_f32 v[46:47], v[26:27], v[154:155], v[46:47] op_sel:[1,0,0] op_sel_hi:[1,1,1]
	v_pk_fma_f32 v[34:35], v[22:23], v[154:155], v[34:35] op_sel:[1,0,0] op_sel_hi:[1,1,1]
	v_pk_fma_f32 v[20:21], v[176:177], v[4:5], v[20:21] op_sel_hi:[1,0,1]
	v_add_f32_dpp v28, v46, v34 row_half_mirror row_mask:0xf bank_mask:0xf
	v_add_f32_dpp v32, v47, v35 row_half_mirror row_mask:0xf bank_mask:0xf
	v_pk_fma_f32 v[22:23], v[178:179], v[4:5], v[22:23] op_sel_hi:[1,0,1]
	v_add_f32_dpp v28, v28, v28 row_ror:8 row_mask:0xf bank_mask:0xf
	v_add_f32_dpp v32, v32, v32 row_ror:8 row_mask:0xf bank_mask:0xf
	v_pk_fma_f32 v[24:25], v[176:177], v[6:7], v[24:25] op_sel_hi:[1,0,1]
	v_add_f32_dpp v28, v28, v28 quad_perm:[1,0,3,2] row_mask:0xf bank_mask:0xf
	v_add_f32_dpp v32, v32, v32 quad_perm:[1,0,3,2] row_mask:0xf bank_mask:0xf
	v_pk_fma_f32 v[26:27], v[178:179], v[6:7], v[26:27] op_sel_hi:[1,0,1]
	v_add_f32_dpp v28, v28, v28 quad_perm:[2,3,0,1] row_mask:0xf bank_mask:0xf
	v_add_f32_dpp v32, v32, v32 quad_perm:[2,3,0,1] row_mask:0xf bank_mask:0xf
	v_pk_fma_f32 v[20:21], v[84:85], v[28:29], v[20:21] op_sel_hi:[1,0,1] neg_lo:[0,1,0] neg_hi:[0,1,0]
	v_mov_b32_dpp v30, v28 row_half_mirror row_mask:0xf bank_mask:0xf
	v_pk_fma_f32 v[22:23], v[86:87], v[28:29], v[22:23] op_sel_hi:[1,0,1] neg_lo:[0,1,0] neg_hi:[0,1,0]
	v_add_f32_e32 v39, v32, v5
	v_pk_fma_f32 v[24:25], v[84:85], v[30:31], v[24:25] op_sel_hi:[1,0,1] neg_lo:[0,1,0] neg_hi:[0,1,0]
	v_pk_fma_f32 v[26:27], v[86:87], v[30:31], v[26:27] op_sel_hi:[1,0,1] neg_lo:[0,1,0] neg_hi:[0,1,0]
	ds_write_b32 v102, v39 offset:2048
	ds_read_b128 v[140:143], v195 offset:4608
	ds_read_b128 v[152:155], v195 offset:12800
	ds_read_b128 v[176:179], v195 offset:20992
	ds_read_b128 v[84:87], v195 offset:37376
	ds_read_b64 v[4:5], v196 offset:9216
	ds_read_b32 v6, v36 offset:9216
	s_waitcnt lgkmcnt(7)
	v_pk_mul_f32 v[46:47], v[24:25], v[144:145] op_sel_hi:[0,1]
	v_pk_mul_f32 v[34:35], v[20:21], v[144:145] op_sel_hi:[0,1]
	v_pk_fma_f32 v[46:47], v[24:25], v[146:147], v[46:47] op_sel:[1,0,0] op_sel_hi:[1,1,1]
	v_pk_fma_f32 v[34:35], v[20:21], v[146:147], v[34:35] op_sel:[1,0,0] op_sel_hi:[1,1,1]
	v_pk_fma_f32 v[46:47], v[26:27], v[156:157], v[46:47] op_sel_hi:[0,1,1]
	v_pk_fma_f32 v[34:35], v[22:23], v[156:157], v[34:35] op_sel_hi:[0,1,1]
	v_pk_fma_f32 v[46:47], v[26:27], v[158:159], v[46:47] op_sel:[1,0,0] op_sel_hi:[1,1,1]
	v_pk_fma_f32 v[34:35], v[22:23], v[158:159], v[34:35] op_sel:[1,0,0] op_sel_hi:[1,1,1]
	v_pk_fma_f32 v[20:21], v[180:181], v[8:9], v[20:21] op_sel_hi:[1,0,1]
	v_add_f32_dpp v28, v46, v34 row_half_mirror row_mask:0xf bank_mask:0xf
	v_add_f32_dpp v32, v47, v35 row_half_mirror row_mask:0xf bank_mask:0xf
	v_pk_fma_f32 v[22:23], v[182:183], v[8:9], v[22:23] op_sel_hi:[1,0,1]
	v_add_f32_dpp v28, v28, v28 row_ror:8 row_mask:0xf bank_mask:0xf
	v_add_f32_dpp v32, v32, v32 row_ror:8 row_mask:0xf bank_mask:0xf
	v_pk_fma_f32 v[24:25], v[180:181], v[10:11], v[24:25] op_sel_hi:[1,0,1]
	v_add_f32_dpp v28, v28, v28 quad_perm:[1,0,3,2] row_mask:0xf bank_mask:0xf
	v_add_f32_dpp v32, v32, v32 quad_perm:[1,0,3,2] row_mask:0xf bank_mask:0xf
	v_pk_fma_f32 v[26:27], v[182:183], v[10:11], v[26:27] op_sel_hi:[1,0,1]
	v_add_f32_dpp v28, v28, v28 quad_perm:[2,3,0,1] row_mask:0xf bank_mask:0xf
	v_add_f32_dpp v32, v32, v32 quad_perm:[2,3,0,1] row_mask:0xf bank_mask:0xf
	v_pk_fma_f32 v[20:21], v[88:89], v[28:29], v[20:21] op_sel_hi:[1,0,1] neg_lo:[0,1,0] neg_hi:[0,1,0]
	v_mov_b32_dpp v30, v28 row_half_mirror row_mask:0xf bank_mask:0xf
	v_pk_fma_f32 v[22:23], v[90:91], v[28:29], v[22:23] op_sel_hi:[1,0,1] neg_lo:[0,1,0] neg_hi:[0,1,0]
	v_add_f32_e32 v39, v32, v9
	v_pk_fma_f32 v[24:25], v[88:89], v[30:31], v[24:25] op_sel_hi:[1,0,1] neg_lo:[0,1,0] neg_hi:[0,1,0]
	v_pk_fma_f32 v[26:27], v[90:91], v[30:31], v[26:27] op_sel_hi:[1,0,1] neg_lo:[0,1,0] neg_hi:[0,1,0]
	ds_write_b32 v102, v39 offset:2176
	ds_read_b128 v[144:147], v195 offset:4864
	ds_read_b128 v[156:159], v195 offset:13056
	ds_read_b128 v[168:171], v195 offset:29440
	ds_read_b128 v[180:183], v195 offset:21248
	ds_read_b128 v[88:91], v195 offset:37632
	ds_read_b64 v[8:9], v196 offset:9728
	ds_read_b32 v10, v36 offset:9728
	s_waitcnt lgkmcnt(8)
	v_pk_mul_f32 v[46:47], v[24:25], v[140:141] op_sel_hi:[0,1]
	v_pk_mul_f32 v[34:35], v[20:21], v[140:141] op_sel_hi:[0,1]
	v_pk_fma_f32 v[46:47], v[24:25], v[142:143], v[46:47] op_sel:[1,0,0] op_sel_hi:[1,1,1]
	v_pk_fma_f32 v[34:35], v[20:21], v[142:143], v[34:35] op_sel:[1,0,0] op_sel_hi:[1,1,1]
	v_pk_fma_f32 v[46:47], v[26:27], v[152:153], v[46:47] op_sel_hi:[0,1,1]
	v_pk_fma_f32 v[34:35], v[22:23], v[152:153], v[34:35] op_sel_hi:[0,1,1]
	v_pk_fma_f32 v[46:47], v[26:27], v[154:155], v[46:47] op_sel:[1,0,0] op_sel_hi:[1,1,1]
	v_pk_fma_f32 v[34:35], v[22:23], v[154:155], v[34:35] op_sel:[1,0,0] op_sel_hi:[1,1,1]
	v_pk_fma_f32 v[20:21], v[176:177], v[4:5], v[20:21] op_sel_hi:[1,0,1]
	v_add_f32_dpp v28, v46, v34 row_half_mirror row_mask:0xf bank_mask:0xf
	v_add_f32_dpp v32, v47, v35 row_half_mirror row_mask:0xf bank_mask:0xf
	v_pk_fma_f32 v[22:23], v[178:179], v[4:5], v[22:23] op_sel_hi:[1,0,1]
	v_add_f32_dpp v28, v28, v28 row_ror:8 row_mask:0xf bank_mask:0xf
	v_add_f32_dpp v32, v32, v32 row_ror:8 row_mask:0xf bank_mask:0xf
	v_pk_fma_f32 v[24:25], v[176:177], v[6:7], v[24:25] op_sel_hi:[1,0,1]
	v_add_f32_dpp v28, v28, v28 quad_perm:[1,0,3,2] row_mask:0xf bank_mask:0xf
	v_add_f32_dpp v32, v32, v32 quad_perm:[1,0,3,2] row_mask:0xf bank_mask:0xf
	v_pk_fma_f32 v[26:27], v[178:179], v[6:7], v[26:27] op_sel_hi:[1,0,1]
	v_add_f32_dpp v28, v28, v28 quad_perm:[2,3,0,1] row_mask:0xf bank_mask:0xf
	v_add_f32_dpp v32, v32, v32 quad_perm:[2,3,0,1] row_mask:0xf bank_mask:0xf
	v_pk_fma_f32 v[20:21], v[84:85], v[28:29], v[20:21] op_sel_hi:[1,0,1] neg_lo:[0,1,0] neg_hi:[0,1,0]
	v_mov_b32_dpp v30, v28 row_half_mirror row_mask:0xf bank_mask:0xf
	v_pk_fma_f32 v[22:23], v[86:87], v[28:29], v[22:23] op_sel_hi:[1,0,1] neg_lo:[0,1,0] neg_hi:[0,1,0]
	v_add_f32_e32 v39, v32, v5
	v_pk_fma_f32 v[24:25], v[84:85], v[30:31], v[24:25] op_sel_hi:[1,0,1] neg_lo:[0,1,0] neg_hi:[0,1,0]
	v_pk_fma_f32 v[26:27], v[86:87], v[30:31], v[26:27] op_sel_hi:[1,0,1] neg_lo:[0,1,0] neg_hi:[0,1,0]
	ds_write_b32 v102, v39 offset:2304
	ds_read_b128 v[140:143], v195 offset:5120
	ds_read_b128 v[152:155], v195 offset:13312
	ds_read_b128 v[176:179], v195 offset:21504
	ds_read_b128 v[84:87], v195 offset:37888
	ds_read_b64 v[4:5], v196 offset:10240
	ds_read_b32 v6, v36 offset:10240
	s_waitcnt lgkmcnt(7)
	v_pk_mul_f32 v[46:47], v[24:25], v[144:145] op_sel_hi:[0,1]
	v_pk_mul_f32 v[34:35], v[20:21], v[144:145] op_sel_hi:[0,1]
	v_pk_fma_f32 v[46:47], v[24:25], v[146:147], v[46:47] op_sel:[1,0,0] op_sel_hi:[1,1,1]
	v_pk_fma_f32 v[34:35], v[20:21], v[146:147], v[34:35] op_sel:[1,0,0] op_sel_hi:[1,1,1]
	v_pk_fma_f32 v[46:47], v[26:27], v[156:157], v[46:47] op_sel_hi:[0,1,1]
	v_pk_fma_f32 v[34:35], v[22:23], v[156:157], v[34:35] op_sel_hi:[0,1,1]
	v_pk_fma_f32 v[46:47], v[26:27], v[158:159], v[46:47] op_sel:[1,0,0] op_sel_hi:[1,1,1]
	v_pk_fma_f32 v[34:35], v[22:23], v[158:159], v[34:35] op_sel:[1,0,0] op_sel_hi:[1,1,1]
	v_pk_mul_f32 v[20:21], v[20:21], v[168:169]
	v_add_f32_dpp v28, v46, v34 row_half_mirror row_mask:0xf bank_mask:0xf
	v_add_f32_dpp v32, v47, v35 row_half_mirror row_mask:0xf bank_mask:0xf
	v_pk_mul_f32 v[22:23], v[22:23], v[170:171]
	v_add_f32_dpp v28, v28, v28 row_ror:8 row_mask:0xf bank_mask:0xf
	v_add_f32_dpp v32, v32, v32 row_ror:8 row_mask:0xf bank_mask:0xf
	v_pk_mul_f32 v[24:25], v[24:25], v[168:169]
	v_add_f32_dpp v28, v28, v28 quad_perm:[1,0,3,2] row_mask:0xf bank_mask:0xf
	v_add_f32_dpp v32, v32, v32 quad_perm:[1,0,3,2] row_mask:0xf bank_mask:0xf
	v_pk_mul_f32 v[26:27], v[26:27], v[170:171]
	v_add_f32_dpp v28, v28, v28 quad_perm:[2,3,0,1] row_mask:0xf bank_mask:0xf
	v_add_f32_dpp v32, v32, v32 quad_perm:[2,3,0,1] row_mask:0xf bank_mask:0xf
	v_pk_fma_f32 v[20:21], v[180:181], v[8:9], v[20:21] op_sel_hi:[1,0,1]
	v_mov_b32_dpp v30, v28 row_half_mirror row_mask:0xf bank_mask:0xf
	v_pk_fma_f32 v[22:23], v[182:183], v[8:9], v[22:23] op_sel_hi:[1,0,1]
	v_pk_fma_f32 v[24:25], v[180:181], v[10:11], v[24:25] op_sel_hi:[1,0,1]
	v_pk_fma_f32 v[26:27], v[182:183], v[10:11], v[26:27] op_sel_hi:[1,0,1]
	v_pk_fma_f32 v[20:21], v[88:89], v[28:29], v[20:21] op_sel_hi:[1,0,1] neg_lo:[0,1,0] neg_hi:[0,1,0]
	v_pk_fma_f32 v[22:23], v[90:91], v[28:29], v[22:23] op_sel_hi:[1,0,1] neg_lo:[0,1,0] neg_hi:[0,1,0]
	v_pk_fma_f32 v[24:25], v[88:89], v[30:31], v[24:25] op_sel_hi:[1,0,1] neg_lo:[0,1,0] neg_hi:[0,1,0]
	v_pk_fma_f32 v[26:27], v[90:91], v[30:31], v[26:27] op_sel_hi:[1,0,1] neg_lo:[0,1,0] neg_hi:[0,1,0]
	v_add_f32_e32 v39, v32, v9
	ds_write_b32 v102, v39 offset:2432
	ds_read_b128 v[144:147], v195 offset:5376
	ds_read_b128 v[156:159], v195 offset:13568
	ds_read_b128 v[180:183], v195 offset:21760
	ds_read_b128 v[88:91], v195 offset:38144
	ds_read_b64 v[8:9], v196 offset:10752
	ds_read_b32 v10, v36 offset:10752
	s_waitcnt lgkmcnt(7)
	v_pk_mul_f32 v[46:47], v[24:25], v[140:141] op_sel_hi:[0,1]
	v_pk_mul_f32 v[34:35], v[20:21], v[140:141] op_sel_hi:[0,1]
	v_pk_fma_f32 v[46:47], v[24:25], v[142:143], v[46:47] op_sel:[1,0,0] op_sel_hi:[1,1,1]
	v_pk_fma_f32 v[34:35], v[20:21], v[142:143], v[34:35] op_sel:[1,0,0] op_sel_hi:[1,1,1]
	v_pk_fma_f32 v[46:47], v[26:27], v[152:153], v[46:47] op_sel_hi:[0,1,1]
	v_pk_fma_f32 v[34:35], v[22:23], v[152:153], v[34:35] op_sel_hi:[0,1,1]
	v_pk_fma_f32 v[46:47], v[26:27], v[154:155], v[46:47] op_sel:[1,0,0] op_sel_hi:[1,1,1]
	v_pk_fma_f32 v[34:35], v[22:23], v[154:155], v[34:35] op_sel:[1,0,0] op_sel_hi:[1,1,1]
	v_pk_fma_f32 v[20:21], v[176:177], v[4:5], v[20:21] op_sel_hi:[1,0,1]
	v_add_f32_dpp v28, v46, v34 row_half_mirror row_mask:0xf bank_mask:0xf
	v_add_f32_dpp v32, v47, v35 row_half_mirror row_mask:0xf bank_mask:0xf
	v_pk_fma_f32 v[22:23], v[178:179], v[4:5], v[22:23] op_sel_hi:[1,0,1]
	v_add_f32_dpp v28, v28, v28 row_ror:8 row_mask:0xf bank_mask:0xf
	v_add_f32_dpp v32, v32, v32 row_ror:8 row_mask:0xf bank_mask:0xf
	v_pk_fma_f32 v[24:25], v[176:177], v[6:7], v[24:25] op_sel_hi:[1,0,1]
	v_add_f32_dpp v28, v28, v28 quad_perm:[1,0,3,2] row_mask:0xf bank_mask:0xf
	v_add_f32_dpp v32, v32, v32 quad_perm:[1,0,3,2] row_mask:0xf bank_mask:0xf
	v_pk_fma_f32 v[26:27], v[178:179], v[6:7], v[26:27] op_sel_hi:[1,0,1]
	v_add_f32_dpp v28, v28, v28 quad_perm:[2,3,0,1] row_mask:0xf bank_mask:0xf
	v_add_f32_dpp v32, v32, v32 quad_perm:[2,3,0,1] row_mask:0xf bank_mask:0xf
	v_pk_fma_f32 v[20:21], v[84:85], v[28:29], v[20:21] op_sel_hi:[1,0,1] neg_lo:[0,1,0] neg_hi:[0,1,0]
	v_mov_b32_dpp v30, v28 row_half_mirror row_mask:0xf bank_mask:0xf
	v_pk_fma_f32 v[22:23], v[86:87], v[28:29], v[22:23] op_sel_hi:[1,0,1] neg_lo:[0,1,0] neg_hi:[0,1,0]
	v_add_f32_e32 v39, v32, v5
	v_pk_fma_f32 v[24:25], v[84:85], v[30:31], v[24:25] op_sel_hi:[1,0,1] neg_lo:[0,1,0] neg_hi:[0,1,0]
	v_pk_fma_f32 v[26:27], v[86:87], v[30:31], v[26:27] op_sel_hi:[1,0,1] neg_lo:[0,1,0] neg_hi:[0,1,0]
	ds_write_b32 v102, v39 offset:2560
	ds_read_b128 v[140:143], v195 offset:5632
	ds_read_b128 v[152:155], v195 offset:13824
	ds_read_b128 v[176:179], v195 offset:22016
	ds_read_b128 v[84:87], v195 offset:38400
	ds_read_b64 v[4:5], v196 offset:11264
	ds_read_b32 v6, v36 offset:11264
	s_waitcnt lgkmcnt(7)
	v_pk_mul_f32 v[46:47], v[24:25], v[144:145] op_sel_hi:[0,1]
	v_pk_mul_f32 v[34:35], v[20:21], v[144:145] op_sel_hi:[0,1]
	v_pk_fma_f32 v[46:47], v[24:25], v[146:147], v[46:47] op_sel:[1,0,0] op_sel_hi:[1,1,1]
	v_pk_fma_f32 v[34:35], v[20:21], v[146:147], v[34:35] op_sel:[1,0,0] op_sel_hi:[1,1,1]
	v_pk_fma_f32 v[46:47], v[26:27], v[156:157], v[46:47] op_sel_hi:[0,1,1]
	v_pk_fma_f32 v[34:35], v[22:23], v[156:157], v[34:35] op_sel_hi:[0,1,1]
	v_pk_fma_f32 v[46:47], v[26:27], v[158:159], v[46:47] op_sel:[1,0,0] op_sel_hi:[1,1,1]
	v_pk_fma_f32 v[34:35], v[22:23], v[158:159], v[34:35] op_sel:[1,0,0] op_sel_hi:[1,1,1]
	v_pk_fma_f32 v[20:21], v[180:181], v[8:9], v[20:21] op_sel_hi:[1,0,1]
	v_add_f32_dpp v28, v46, v34 row_half_mirror row_mask:0xf bank_mask:0xf
	v_add_f32_dpp v32, v47, v35 row_half_mirror row_mask:0xf bank_mask:0xf
	v_pk_fma_f32 v[22:23], v[182:183], v[8:9], v[22:23] op_sel_hi:[1,0,1]
	v_add_f32_dpp v28, v28, v28 row_ror:8 row_mask:0xf bank_mask:0xf
	v_add_f32_dpp v32, v32, v32 row_ror:8 row_mask:0xf bank_mask:0xf
	v_pk_fma_f32 v[24:25], v[180:181], v[10:11], v[24:25] op_sel_hi:[1,0,1]
	v_add_f32_dpp v28, v28, v28 quad_perm:[1,0,3,2] row_mask:0xf bank_mask:0xf
	v_add_f32_dpp v32, v32, v32 quad_perm:[1,0,3,2] row_mask:0xf bank_mask:0xf
	v_pk_fma_f32 v[26:27], v[182:183], v[10:11], v[26:27] op_sel_hi:[1,0,1]
	v_add_f32_dpp v28, v28, v28 quad_perm:[2,3,0,1] row_mask:0xf bank_mask:0xf
	v_add_f32_dpp v32, v32, v32 quad_perm:[2,3,0,1] row_mask:0xf bank_mask:0xf
	v_pk_fma_f32 v[20:21], v[88:89], v[28:29], v[20:21] op_sel_hi:[1,0,1] neg_lo:[0,1,0] neg_hi:[0,1,0]
	v_mov_b32_dpp v30, v28 row_half_mirror row_mask:0xf bank_mask:0xf
	v_pk_fma_f32 v[22:23], v[90:91], v[28:29], v[22:23] op_sel_hi:[1,0,1] neg_lo:[0,1,0] neg_hi:[0,1,0]
	v_add_f32_e32 v39, v32, v9
	v_pk_fma_f32 v[24:25], v[88:89], v[30:31], v[24:25] op_sel_hi:[1,0,1] neg_lo:[0,1,0] neg_hi:[0,1,0]
	v_pk_fma_f32 v[26:27], v[90:91], v[30:31], v[26:27] op_sel_hi:[1,0,1] neg_lo:[0,1,0] neg_hi:[0,1,0]
	ds_write_b32 v102, v39 offset:2688
	ds_read_b128 v[144:147], v195 offset:5888
	ds_read_b128 v[156:159], v195 offset:14080
	ds_read_b128 v[168:171], v195 offset:30464
	ds_read_b128 v[180:183], v195 offset:22272
	ds_read_b128 v[88:91], v195 offset:38656
	ds_read_b64 v[8:9], v196 offset:11776
	ds_read_b32 v10, v36 offset:11776
	s_waitcnt lgkmcnt(8)
	v_pk_mul_f32 v[46:47], v[24:25], v[140:141] op_sel_hi:[0,1]
	v_pk_mul_f32 v[34:35], v[20:21], v[140:141] op_sel_hi:[0,1]
	v_pk_fma_f32 v[46:47], v[24:25], v[142:143], v[46:47] op_sel:[1,0,0] op_sel_hi:[1,1,1]
	v_pk_fma_f32 v[34:35], v[20:21], v[142:143], v[34:35] op_sel:[1,0,0] op_sel_hi:[1,1,1]
	v_pk_fma_f32 v[46:47], v[26:27], v[152:153], v[46:47] op_sel_hi:[0,1,1]
	v_pk_fma_f32 v[34:35], v[22:23], v[152:153], v[34:35] op_sel_hi:[0,1,1]
	v_pk_fma_f32 v[46:47], v[26:27], v[154:155], v[46:47] op_sel:[1,0,0] op_sel_hi:[1,1,1]
	v_pk_fma_f32 v[34:35], v[22:23], v[154:155], v[34:35] op_sel:[1,0,0] op_sel_hi:[1,1,1]
	v_pk_fma_f32 v[20:21], v[176:177], v[4:5], v[20:21] op_sel_hi:[1,0,1]
	v_add_f32_dpp v28, v46, v34 row_half_mirror row_mask:0xf bank_mask:0xf
	v_add_f32_dpp v32, v47, v35 row_half_mirror row_mask:0xf bank_mask:0xf
	v_pk_fma_f32 v[22:23], v[178:179], v[4:5], v[22:23] op_sel_hi:[1,0,1]
	v_add_f32_dpp v28, v28, v28 row_ror:8 row_mask:0xf bank_mask:0xf
	v_add_f32_dpp v32, v32, v32 row_ror:8 row_mask:0xf bank_mask:0xf
	v_pk_fma_f32 v[24:25], v[176:177], v[6:7], v[24:25] op_sel_hi:[1,0,1]
	v_add_f32_dpp v28, v28, v28 quad_perm:[1,0,3,2] row_mask:0xf bank_mask:0xf
	v_add_f32_dpp v32, v32, v32 quad_perm:[1,0,3,2] row_mask:0xf bank_mask:0xf
	v_pk_fma_f32 v[26:27], v[178:179], v[6:7], v[26:27] op_sel_hi:[1,0,1]
	v_add_f32_dpp v28, v28, v28 quad_perm:[2,3,0,1] row_mask:0xf bank_mask:0xf
	v_add_f32_dpp v32, v32, v32 quad_perm:[2,3,0,1] row_mask:0xf bank_mask:0xf
	v_pk_fma_f32 v[20:21], v[84:85], v[28:29], v[20:21] op_sel_hi:[1,0,1] neg_lo:[0,1,0] neg_hi:[0,1,0]
	v_mov_b32_dpp v30, v28 row_half_mirror row_mask:0xf bank_mask:0xf
	v_pk_fma_f32 v[22:23], v[86:87], v[28:29], v[22:23] op_sel_hi:[1,0,1] neg_lo:[0,1,0] neg_hi:[0,1,0]
	v_add_f32_e32 v39, v32, v5
	v_pk_fma_f32 v[24:25], v[84:85], v[30:31], v[24:25] op_sel_hi:[1,0,1] neg_lo:[0,1,0] neg_hi:[0,1,0]
	v_pk_fma_f32 v[26:27], v[86:87], v[30:31], v[26:27] op_sel_hi:[1,0,1] neg_lo:[0,1,0] neg_hi:[0,1,0]
	ds_write_b32 v102, v39 offset:2816
	ds_read_b128 v[140:143], v195 offset:6144
	ds_read_b128 v[152:155], v195 offset:14336
	ds_read_b128 v[176:179], v195 offset:22528
	ds_read_b128 v[84:87], v195 offset:38912
	ds_read_b64 v[4:5], v196 offset:12288
	ds_read_b32 v6, v36 offset:12288
	s_waitcnt lgkmcnt(7)
	v_pk_mul_f32 v[46:47], v[24:25], v[144:145] op_sel_hi:[0,1]
	v_pk_mul_f32 v[34:35], v[20:21], v[144:145] op_sel_hi:[0,1]
	v_pk_fma_f32 v[46:47], v[24:25], v[146:147], v[46:47] op_sel:[1,0,0] op_sel_hi:[1,1,1]
	v_pk_fma_f32 v[34:35], v[20:21], v[146:147], v[34:35] op_sel:[1,0,0] op_sel_hi:[1,1,1]
	v_pk_fma_f32 v[46:47], v[26:27], v[156:157], v[46:47] op_sel_hi:[0,1,1]
	v_pk_fma_f32 v[34:35], v[22:23], v[156:157], v[34:35] op_sel_hi:[0,1,1]
	v_pk_fma_f32 v[46:47], v[26:27], v[158:159], v[46:47] op_sel:[1,0,0] op_sel_hi:[1,1,1]
	v_pk_fma_f32 v[34:35], v[22:23], v[158:159], v[34:35] op_sel:[1,0,0] op_sel_hi:[1,1,1]
	v_pk_mul_f32 v[20:21], v[20:21], v[168:169]
	v_add_f32_dpp v28, v46, v34 row_half_mirror row_mask:0xf bank_mask:0xf
	v_add_f32_dpp v32, v47, v35 row_half_mirror row_mask:0xf bank_mask:0xf
	v_pk_mul_f32 v[22:23], v[22:23], v[170:171]
	v_add_f32_dpp v28, v28, v28 row_ror:8 row_mask:0xf bank_mask:0xf
	v_add_f32_dpp v32, v32, v32 row_ror:8 row_mask:0xf bank_mask:0xf
	v_pk_mul_f32 v[24:25], v[24:25], v[168:169]
	v_add_f32_dpp v28, v28, v28 quad_perm:[1,0,3,2] row_mask:0xf bank_mask:0xf
	v_add_f32_dpp v32, v32, v32 quad_perm:[1,0,3,2] row_mask:0xf bank_mask:0xf
	v_pk_mul_f32 v[26:27], v[26:27], v[170:171]
	v_add_f32_dpp v28, v28, v28 quad_perm:[2,3,0,1] row_mask:0xf bank_mask:0xf
	v_add_f32_dpp v32, v32, v32 quad_perm:[2,3,0,1] row_mask:0xf bank_mask:0xf
	v_pk_fma_f32 v[20:21], v[180:181], v[8:9], v[20:21] op_sel_hi:[1,0,1]
	v_mov_b32_dpp v30, v28 row_half_mirror row_mask:0xf bank_mask:0xf
	v_pk_fma_f32 v[22:23], v[182:183], v[8:9], v[22:23] op_sel_hi:[1,0,1]
	v_pk_fma_f32 v[24:25], v[180:181], v[10:11], v[24:25] op_sel_hi:[1,0,1]
	v_pk_fma_f32 v[26:27], v[182:183], v[10:11], v[26:27] op_sel_hi:[1,0,1]
	v_pk_fma_f32 v[20:21], v[88:89], v[28:29], v[20:21] op_sel_hi:[1,0,1] neg_lo:[0,1,0] neg_hi:[0,1,0]
	v_pk_fma_f32 v[22:23], v[90:91], v[28:29], v[22:23] op_sel_hi:[1,0,1] neg_lo:[0,1,0] neg_hi:[0,1,0]
	v_pk_fma_f32 v[24:25], v[88:89], v[30:31], v[24:25] op_sel_hi:[1,0,1] neg_lo:[0,1,0] neg_hi:[0,1,0]
	v_pk_fma_f32 v[26:27], v[90:91], v[30:31], v[26:27] op_sel_hi:[1,0,1] neg_lo:[0,1,0] neg_hi:[0,1,0]
	v_add_f32_e32 v39, v32, v9
	ds_write_b32 v102, v39 offset:2944
	ds_read_b128 v[144:147], v195 offset:6400
	ds_read_b128 v[156:159], v195 offset:14592
	ds_read_b128 v[180:183], v195 offset:22784
	ds_read_b128 v[88:91], v195 offset:39168
	ds_read_b64 v[8:9], v196 offset:12800
	ds_read_b32 v10, v36 offset:12800
	s_waitcnt lgkmcnt(7)
	v_pk_mul_f32 v[46:47], v[24:25], v[140:141] op_sel_hi:[0,1]
	v_pk_mul_f32 v[34:35], v[20:21], v[140:141] op_sel_hi:[0,1]
	v_pk_fma_f32 v[46:47], v[24:25], v[142:143], v[46:47] op_sel:[1,0,0] op_sel_hi:[1,1,1]
	v_pk_fma_f32 v[34:35], v[20:21], v[142:143], v[34:35] op_sel:[1,0,0] op_sel_hi:[1,1,1]
	v_pk_fma_f32 v[46:47], v[26:27], v[152:153], v[46:47] op_sel_hi:[0,1,1]
	v_pk_fma_f32 v[34:35], v[22:23], v[152:153], v[34:35] op_sel_hi:[0,1,1]
	v_pk_fma_f32 v[46:47], v[26:27], v[154:155], v[46:47] op_sel:[1,0,0] op_sel_hi:[1,1,1]
	v_pk_fma_f32 v[34:35], v[22:23], v[154:155], v[34:35] op_sel:[1,0,0] op_sel_hi:[1,1,1]
	v_pk_fma_f32 v[20:21], v[176:177], v[4:5], v[20:21] op_sel_hi:[1,0,1]
	v_add_f32_dpp v28, v46, v34 row_half_mirror row_mask:0xf bank_mask:0xf
	v_add_f32_dpp v32, v47, v35 row_half_mirror row_mask:0xf bank_mask:0xf
	v_pk_fma_f32 v[22:23], v[178:179], v[4:5], v[22:23] op_sel_hi:[1,0,1]
	v_add_f32_dpp v28, v28, v28 row_ror:8 row_mask:0xf bank_mask:0xf
	v_add_f32_dpp v32, v32, v32 row_ror:8 row_mask:0xf bank_mask:0xf
	v_pk_fma_f32 v[24:25], v[176:177], v[6:7], v[24:25] op_sel_hi:[1,0,1]
	v_add_f32_dpp v28, v28, v28 quad_perm:[1,0,3,2] row_mask:0xf bank_mask:0xf
	v_add_f32_dpp v32, v32, v32 quad_perm:[1,0,3,2] row_mask:0xf bank_mask:0xf
	v_pk_fma_f32 v[26:27], v[178:179], v[6:7], v[26:27] op_sel_hi:[1,0,1]
	v_add_f32_dpp v28, v28, v28 quad_perm:[2,3,0,1] row_mask:0xf bank_mask:0xf
	v_add_f32_dpp v32, v32, v32 quad_perm:[2,3,0,1] row_mask:0xf bank_mask:0xf
	v_pk_fma_f32 v[20:21], v[84:85], v[28:29], v[20:21] op_sel_hi:[1,0,1] neg_lo:[0,1,0] neg_hi:[0,1,0]
	v_mov_b32_dpp v30, v28 row_half_mirror row_mask:0xf bank_mask:0xf
	v_pk_fma_f32 v[22:23], v[86:87], v[28:29], v[22:23] op_sel_hi:[1,0,1] neg_lo:[0,1,0] neg_hi:[0,1,0]
	v_add_f32_e32 v39, v32, v5
	v_pk_fma_f32 v[24:25], v[84:85], v[30:31], v[24:25] op_sel_hi:[1,0,1] neg_lo:[0,1,0] neg_hi:[0,1,0]
	v_pk_fma_f32 v[26:27], v[86:87], v[30:31], v[26:27] op_sel_hi:[1,0,1] neg_lo:[0,1,0] neg_hi:[0,1,0]
	ds_write_b32 v102, v39 offset:3072
	ds_read_b128 v[140:143], v195 offset:6656
	ds_read_b128 v[152:155], v195 offset:14848
	ds_read_b128 v[176:179], v195 offset:23040
	ds_read_b128 v[84:87], v195 offset:39424
	ds_read_b64 v[4:5], v196 offset:13312
	ds_read_b32 v6, v36 offset:13312
	s_waitcnt lgkmcnt(7)
	v_pk_mul_f32 v[46:47], v[24:25], v[144:145] op_sel_hi:[0,1]
	v_pk_mul_f32 v[34:35], v[20:21], v[144:145] op_sel_hi:[0,1]
	v_pk_fma_f32 v[46:47], v[24:25], v[146:147], v[46:47] op_sel:[1,0,0] op_sel_hi:[1,1,1]
	v_pk_fma_f32 v[34:35], v[20:21], v[146:147], v[34:35] op_sel:[1,0,0] op_sel_hi:[1,1,1]
	v_pk_fma_f32 v[46:47], v[26:27], v[156:157], v[46:47] op_sel_hi:[0,1,1]
	v_pk_fma_f32 v[34:35], v[22:23], v[156:157], v[34:35] op_sel_hi:[0,1,1]
	v_pk_fma_f32 v[46:47], v[26:27], v[158:159], v[46:47] op_sel:[1,0,0] op_sel_hi:[1,1,1]
	v_pk_fma_f32 v[34:35], v[22:23], v[158:159], v[34:35] op_sel:[1,0,0] op_sel_hi:[1,1,1]
	v_pk_fma_f32 v[20:21], v[180:181], v[8:9], v[20:21] op_sel_hi:[1,0,1]
	v_add_f32_dpp v28, v46, v34 row_half_mirror row_mask:0xf bank_mask:0xf
	v_add_f32_dpp v32, v47, v35 row_half_mirror row_mask:0xf bank_mask:0xf
	v_pk_fma_f32 v[22:23], v[182:183], v[8:9], v[22:23] op_sel_hi:[1,0,1]
	v_add_f32_dpp v28, v28, v28 row_ror:8 row_mask:0xf bank_mask:0xf
	v_add_f32_dpp v32, v32, v32 row_ror:8 row_mask:0xf bank_mask:0xf
	v_pk_fma_f32 v[24:25], v[180:181], v[10:11], v[24:25] op_sel_hi:[1,0,1]
	v_add_f32_dpp v28, v28, v28 quad_perm:[1,0,3,2] row_mask:0xf bank_mask:0xf
	v_add_f32_dpp v32, v32, v32 quad_perm:[1,0,3,2] row_mask:0xf bank_mask:0xf
	v_pk_fma_f32 v[26:27], v[182:183], v[10:11], v[26:27] op_sel_hi:[1,0,1]
	v_add_f32_dpp v28, v28, v28 quad_perm:[2,3,0,1] row_mask:0xf bank_mask:0xf
	v_add_f32_dpp v32, v32, v32 quad_perm:[2,3,0,1] row_mask:0xf bank_mask:0xf
	v_pk_fma_f32 v[20:21], v[88:89], v[28:29], v[20:21] op_sel_hi:[1,0,1] neg_lo:[0,1,0] neg_hi:[0,1,0]
	v_mov_b32_dpp v30, v28 row_half_mirror row_mask:0xf bank_mask:0xf
	v_pk_fma_f32 v[22:23], v[90:91], v[28:29], v[22:23] op_sel_hi:[1,0,1] neg_lo:[0,1,0] neg_hi:[0,1,0]
	v_add_f32_e32 v39, v32, v9
	v_pk_fma_f32 v[24:25], v[88:89], v[30:31], v[24:25] op_sel_hi:[1,0,1] neg_lo:[0,1,0] neg_hi:[0,1,0]
	v_pk_fma_f32 v[26:27], v[90:91], v[30:31], v[26:27] op_sel_hi:[1,0,1] neg_lo:[0,1,0] neg_hi:[0,1,0]
	ds_write_b32 v102, v39 offset:3200
	ds_read_b128 v[144:147], v195 offset:6912
	ds_read_b128 v[156:159], v195 offset:15104
	ds_read_b128 v[168:171], v195 offset:31488
	ds_read_b128 v[180:183], v195 offset:23296
	ds_read_b128 v[88:91], v195 offset:39680
	ds_read_b64 v[8:9], v196 offset:13824
	ds_read_b32 v10, v36 offset:13824
	s_waitcnt lgkmcnt(8)
	v_pk_mul_f32 v[46:47], v[24:25], v[140:141] op_sel_hi:[0,1]
	v_pk_mul_f32 v[34:35], v[20:21], v[140:141] op_sel_hi:[0,1]
	v_pk_fma_f32 v[46:47], v[24:25], v[142:143], v[46:47] op_sel:[1,0,0] op_sel_hi:[1,1,1]
	v_pk_fma_f32 v[34:35], v[20:21], v[142:143], v[34:35] op_sel:[1,0,0] op_sel_hi:[1,1,1]
	v_pk_fma_f32 v[46:47], v[26:27], v[152:153], v[46:47] op_sel_hi:[0,1,1]
	v_pk_fma_f32 v[34:35], v[22:23], v[152:153], v[34:35] op_sel_hi:[0,1,1]
	v_pk_fma_f32 v[46:47], v[26:27], v[154:155], v[46:47] op_sel:[1,0,0] op_sel_hi:[1,1,1]
	v_pk_fma_f32 v[34:35], v[22:23], v[154:155], v[34:35] op_sel:[1,0,0] op_sel_hi:[1,1,1]
	v_pk_fma_f32 v[20:21], v[176:177], v[4:5], v[20:21] op_sel_hi:[1,0,1]
	v_add_f32_dpp v28, v46, v34 row_half_mirror row_mask:0xf bank_mask:0xf
	v_add_f32_dpp v32, v47, v35 row_half_mirror row_mask:0xf bank_mask:0xf
	v_pk_fma_f32 v[22:23], v[178:179], v[4:5], v[22:23] op_sel_hi:[1,0,1]
	v_add_f32_dpp v28, v28, v28 row_ror:8 row_mask:0xf bank_mask:0xf
	v_add_f32_dpp v32, v32, v32 row_ror:8 row_mask:0xf bank_mask:0xf
	v_pk_fma_f32 v[24:25], v[176:177], v[6:7], v[24:25] op_sel_hi:[1,0,1]
	v_add_f32_dpp v28, v28, v28 quad_perm:[1,0,3,2] row_mask:0xf bank_mask:0xf
	v_add_f32_dpp v32, v32, v32 quad_perm:[1,0,3,2] row_mask:0xf bank_mask:0xf
	v_pk_fma_f32 v[26:27], v[178:179], v[6:7], v[26:27] op_sel_hi:[1,0,1]
	v_add_f32_dpp v28, v28, v28 quad_perm:[2,3,0,1] row_mask:0xf bank_mask:0xf
	v_add_f32_dpp v32, v32, v32 quad_perm:[2,3,0,1] row_mask:0xf bank_mask:0xf
	v_pk_fma_f32 v[20:21], v[84:85], v[28:29], v[20:21] op_sel_hi:[1,0,1] neg_lo:[0,1,0] neg_hi:[0,1,0]
	v_mov_b32_dpp v30, v28 row_half_mirror row_mask:0xf bank_mask:0xf
	v_pk_fma_f32 v[22:23], v[86:87], v[28:29], v[22:23] op_sel_hi:[1,0,1] neg_lo:[0,1,0] neg_hi:[0,1,0]
	v_add_f32_e32 v39, v32, v5
	v_pk_fma_f32 v[24:25], v[84:85], v[30:31], v[24:25] op_sel_hi:[1,0,1] neg_lo:[0,1,0] neg_hi:[0,1,0]
	v_pk_fma_f32 v[26:27], v[86:87], v[30:31], v[26:27] op_sel_hi:[1,0,1] neg_lo:[0,1,0] neg_hi:[0,1,0]
	ds_write_b32 v102, v39 offset:3328
	ds_read_b128 v[140:143], v195 offset:7168
	ds_read_b128 v[152:155], v195 offset:15360
	ds_read_b128 v[176:179], v195 offset:23552
	ds_read_b128 v[84:87], v195 offset:39936
	ds_read_b64 v[4:5], v196 offset:14336
	ds_read_b32 v6, v36 offset:14336
	s_waitcnt lgkmcnt(7)
	v_pk_mul_f32 v[46:47], v[24:25], v[144:145] op_sel_hi:[0,1]
	v_pk_mul_f32 v[34:35], v[20:21], v[144:145] op_sel_hi:[0,1]
	v_pk_fma_f32 v[46:47], v[24:25], v[146:147], v[46:47] op_sel:[1,0,0] op_sel_hi:[1,1,1]
	v_pk_fma_f32 v[34:35], v[20:21], v[146:147], v[34:35] op_sel:[1,0,0] op_sel_hi:[1,1,1]
	v_pk_fma_f32 v[46:47], v[26:27], v[156:157], v[46:47] op_sel_hi:[0,1,1]
	v_pk_fma_f32 v[34:35], v[22:23], v[156:157], v[34:35] op_sel_hi:[0,1,1]
	v_pk_fma_f32 v[46:47], v[26:27], v[158:159], v[46:47] op_sel:[1,0,0] op_sel_hi:[1,1,1]
	v_pk_fma_f32 v[34:35], v[22:23], v[158:159], v[34:35] op_sel:[1,0,0] op_sel_hi:[1,1,1]
	v_pk_mul_f32 v[20:21], v[20:21], v[168:169]
	v_add_f32_dpp v28, v46, v34 row_half_mirror row_mask:0xf bank_mask:0xf
	v_add_f32_dpp v32, v47, v35 row_half_mirror row_mask:0xf bank_mask:0xf
	v_pk_mul_f32 v[22:23], v[22:23], v[170:171]
	v_add_f32_dpp v28, v28, v28 row_ror:8 row_mask:0xf bank_mask:0xf
	v_add_f32_dpp v32, v32, v32 row_ror:8 row_mask:0xf bank_mask:0xf
	v_pk_mul_f32 v[24:25], v[24:25], v[168:169]
	v_add_f32_dpp v28, v28, v28 quad_perm:[1,0,3,2] row_mask:0xf bank_mask:0xf
	v_add_f32_dpp v32, v32, v32 quad_perm:[1,0,3,2] row_mask:0xf bank_mask:0xf
	v_pk_mul_f32 v[26:27], v[26:27], v[170:171]
	v_add_f32_dpp v28, v28, v28 quad_perm:[2,3,0,1] row_mask:0xf bank_mask:0xf
	v_add_f32_dpp v32, v32, v32 quad_perm:[2,3,0,1] row_mask:0xf bank_mask:0xf
	v_pk_fma_f32 v[20:21], v[180:181], v[8:9], v[20:21] op_sel_hi:[1,0,1]
	v_mov_b32_dpp v30, v28 row_half_mirror row_mask:0xf bank_mask:0xf
	v_pk_fma_f32 v[22:23], v[182:183], v[8:9], v[22:23] op_sel_hi:[1,0,1]
	v_pk_fma_f32 v[24:25], v[180:181], v[10:11], v[24:25] op_sel_hi:[1,0,1]
	v_pk_fma_f32 v[26:27], v[182:183], v[10:11], v[26:27] op_sel_hi:[1,0,1]
	v_pk_fma_f32 v[20:21], v[88:89], v[28:29], v[20:21] op_sel_hi:[1,0,1] neg_lo:[0,1,0] neg_hi:[0,1,0]
	v_pk_fma_f32 v[22:23], v[90:91], v[28:29], v[22:23] op_sel_hi:[1,0,1] neg_lo:[0,1,0] neg_hi:[0,1,0]
	v_pk_fma_f32 v[24:25], v[88:89], v[30:31], v[24:25] op_sel_hi:[1,0,1] neg_lo:[0,1,0] neg_hi:[0,1,0]
	v_pk_fma_f32 v[26:27], v[90:91], v[30:31], v[26:27] op_sel_hi:[1,0,1] neg_lo:[0,1,0] neg_hi:[0,1,0]
	v_add_f32_e32 v39, v32, v9
	ds_write_b32 v102, v39 offset:3456
	ds_read_b128 v[144:147], v195 offset:7424
	ds_read_b128 v[156:159], v195 offset:15616
	ds_read_b128 v[180:183], v195 offset:23808
	ds_read_b128 v[88:91], v195 offset:40192
	ds_read_b64 v[8:9], v196 offset:14848
	ds_read_b32 v10, v36 offset:14848
	s_waitcnt lgkmcnt(7)
	v_pk_mul_f32 v[46:47], v[24:25], v[140:141] op_sel_hi:[0,1]
	v_pk_mul_f32 v[34:35], v[20:21], v[140:141] op_sel_hi:[0,1]
	v_pk_fma_f32 v[46:47], v[24:25], v[142:143], v[46:47] op_sel:[1,0,0] op_sel_hi:[1,1,1]
	v_pk_fma_f32 v[34:35], v[20:21], v[142:143], v[34:35] op_sel:[1,0,0] op_sel_hi:[1,1,1]
	v_pk_fma_f32 v[46:47], v[26:27], v[152:153], v[46:47] op_sel_hi:[0,1,1]
	v_pk_fma_f32 v[34:35], v[22:23], v[152:153], v[34:35] op_sel_hi:[0,1,1]
	v_pk_fma_f32 v[46:47], v[26:27], v[154:155], v[46:47] op_sel:[1,0,0] op_sel_hi:[1,1,1]
	v_pk_fma_f32 v[34:35], v[22:23], v[154:155], v[34:35] op_sel:[1,0,0] op_sel_hi:[1,1,1]
	v_pk_fma_f32 v[20:21], v[176:177], v[4:5], v[20:21] op_sel_hi:[1,0,1]
	v_add_f32_dpp v28, v46, v34 row_half_mirror row_mask:0xf bank_mask:0xf
	v_add_f32_dpp v32, v47, v35 row_half_mirror row_mask:0xf bank_mask:0xf
	v_pk_fma_f32 v[22:23], v[178:179], v[4:5], v[22:23] op_sel_hi:[1,0,1]
	v_add_f32_dpp v28, v28, v28 row_ror:8 row_mask:0xf bank_mask:0xf
	v_add_f32_dpp v32, v32, v32 row_ror:8 row_mask:0xf bank_mask:0xf
	v_pk_fma_f32 v[24:25], v[176:177], v[6:7], v[24:25] op_sel_hi:[1,0,1]
	v_add_f32_dpp v28, v28, v28 quad_perm:[1,0,3,2] row_mask:0xf bank_mask:0xf
	v_add_f32_dpp v32, v32, v32 quad_perm:[1,0,3,2] row_mask:0xf bank_mask:0xf
	v_pk_fma_f32 v[26:27], v[178:179], v[6:7], v[26:27] op_sel_hi:[1,0,1]
	v_add_f32_dpp v28, v28, v28 quad_perm:[2,3,0,1] row_mask:0xf bank_mask:0xf
	v_add_f32_dpp v32, v32, v32 quad_perm:[2,3,0,1] row_mask:0xf bank_mask:0xf
	v_pk_fma_f32 v[20:21], v[84:85], v[28:29], v[20:21] op_sel_hi:[1,0,1] neg_lo:[0,1,0] neg_hi:[0,1,0]
	v_mov_b32_dpp v30, v28 row_half_mirror row_mask:0xf bank_mask:0xf
	v_pk_fma_f32 v[22:23], v[86:87], v[28:29], v[22:23] op_sel_hi:[1,0,1] neg_lo:[0,1,0] neg_hi:[0,1,0]
	v_add_f32_e32 v39, v32, v5
	v_pk_fma_f32 v[24:25], v[84:85], v[30:31], v[24:25] op_sel_hi:[1,0,1] neg_lo:[0,1,0] neg_hi:[0,1,0]
	v_pk_fma_f32 v[26:27], v[86:87], v[30:31], v[26:27] op_sel_hi:[1,0,1] neg_lo:[0,1,0] neg_hi:[0,1,0]
	ds_write_b32 v102, v39 offset:3584
	ds_read_b128 v[140:143], v195 offset:7680
	ds_read_b128 v[152:155], v195 offset:15872
	ds_read_b128 v[176:179], v195 offset:24064
	ds_read_b128 v[84:87], v195 offset:40448
	ds_read_b64 v[4:5], v196 offset:15360
	ds_read_b32 v6, v36 offset:15360
	s_waitcnt lgkmcnt(7)
	v_pk_mul_f32 v[46:47], v[24:25], v[144:145] op_sel_hi:[0,1]
	v_pk_mul_f32 v[34:35], v[20:21], v[144:145] op_sel_hi:[0,1]
	v_pk_fma_f32 v[46:47], v[24:25], v[146:147], v[46:47] op_sel:[1,0,0] op_sel_hi:[1,1,1]
	v_pk_fma_f32 v[34:35], v[20:21], v[146:147], v[34:35] op_sel:[1,0,0] op_sel_hi:[1,1,1]
	v_pk_fma_f32 v[46:47], v[26:27], v[156:157], v[46:47] op_sel_hi:[0,1,1]
	v_pk_fma_f32 v[34:35], v[22:23], v[156:157], v[34:35] op_sel_hi:[0,1,1]
	v_pk_fma_f32 v[46:47], v[26:27], v[158:159], v[46:47] op_sel:[1,0,0] op_sel_hi:[1,1,1]
	v_pk_fma_f32 v[34:35], v[22:23], v[158:159], v[34:35] op_sel:[1,0,0] op_sel_hi:[1,1,1]
	v_pk_fma_f32 v[20:21], v[180:181], v[8:9], v[20:21] op_sel_hi:[1,0,1]
	v_add_f32_dpp v28, v46, v34 row_half_mirror row_mask:0xf bank_mask:0xf
	v_add_f32_dpp v32, v47, v35 row_half_mirror row_mask:0xf bank_mask:0xf
	v_pk_fma_f32 v[22:23], v[182:183], v[8:9], v[22:23] op_sel_hi:[1,0,1]
	v_add_f32_dpp v28, v28, v28 row_ror:8 row_mask:0xf bank_mask:0xf
	v_add_f32_dpp v32, v32, v32 row_ror:8 row_mask:0xf bank_mask:0xf
	v_pk_fma_f32 v[24:25], v[180:181], v[10:11], v[24:25] op_sel_hi:[1,0,1]
	v_add_f32_dpp v28, v28, v28 quad_perm:[1,0,3,2] row_mask:0xf bank_mask:0xf
	v_add_f32_dpp v32, v32, v32 quad_perm:[1,0,3,2] row_mask:0xf bank_mask:0xf
	v_pk_fma_f32 v[26:27], v[182:183], v[10:11], v[26:27] op_sel_hi:[1,0,1]
	v_add_f32_dpp v28, v28, v28 quad_perm:[2,3,0,1] row_mask:0xf bank_mask:0xf
	v_add_f32_dpp v32, v32, v32 quad_perm:[2,3,0,1] row_mask:0xf bank_mask:0xf
	v_pk_fma_f32 v[20:21], v[88:89], v[28:29], v[20:21] op_sel_hi:[1,0,1] neg_lo:[0,1,0] neg_hi:[0,1,0]
	v_mov_b32_dpp v30, v28 row_half_mirror row_mask:0xf bank_mask:0xf
	v_pk_fma_f32 v[22:23], v[90:91], v[28:29], v[22:23] op_sel_hi:[1,0,1] neg_lo:[0,1,0] neg_hi:[0,1,0]
	v_add_f32_e32 v39, v32, v9
	v_pk_fma_f32 v[24:25], v[88:89], v[30:31], v[24:25] op_sel_hi:[1,0,1] neg_lo:[0,1,0] neg_hi:[0,1,0]
	v_pk_fma_f32 v[26:27], v[90:91], v[30:31], v[26:27] op_sel_hi:[1,0,1] neg_lo:[0,1,0] neg_hi:[0,1,0]
	ds_write_b32 v102, v39 offset:3712
	ds_read_b128 v[144:147], v195 offset:7936
	ds_read_b128 v[156:159], v195 offset:16128
	ds_read_b128 v[168:171], v195 offset:32512
	ds_read_b128 v[180:183], v195 offset:24320
	ds_read_b128 v[88:91], v195 offset:40704
	ds_read_b64 v[8:9], v196 offset:15872
	ds_read_b32 v10, v36 offset:15872
	s_waitcnt lgkmcnt(8)
	v_pk_mul_f32 v[46:47], v[24:25], v[140:141] op_sel_hi:[0,1]
	v_pk_mul_f32 v[34:35], v[20:21], v[140:141] op_sel_hi:[0,1]
	v_pk_fma_f32 v[46:47], v[24:25], v[142:143], v[46:47] op_sel:[1,0,0] op_sel_hi:[1,1,1]
	v_pk_fma_f32 v[34:35], v[20:21], v[142:143], v[34:35] op_sel:[1,0,0] op_sel_hi:[1,1,1]
	v_pk_fma_f32 v[46:47], v[26:27], v[152:153], v[46:47] op_sel_hi:[0,1,1]
	v_pk_fma_f32 v[34:35], v[22:23], v[152:153], v[34:35] op_sel_hi:[0,1,1]
	v_pk_fma_f32 v[46:47], v[26:27], v[154:155], v[46:47] op_sel:[1,0,0] op_sel_hi:[1,1,1]
	v_pk_fma_f32 v[34:35], v[22:23], v[154:155], v[34:35] op_sel:[1,0,0] op_sel_hi:[1,1,1]
	v_pk_fma_f32 v[20:21], v[176:177], v[4:5], v[20:21] op_sel_hi:[1,0,1]
	v_add_f32_dpp v28, v46, v34 row_half_mirror row_mask:0xf bank_mask:0xf
	v_add_f32_dpp v32, v47, v35 row_half_mirror row_mask:0xf bank_mask:0xf
	v_pk_fma_f32 v[22:23], v[178:179], v[4:5], v[22:23] op_sel_hi:[1,0,1]
	v_add_f32_dpp v28, v28, v28 row_ror:8 row_mask:0xf bank_mask:0xf
	v_add_f32_dpp v32, v32, v32 row_ror:8 row_mask:0xf bank_mask:0xf
	v_pk_fma_f32 v[24:25], v[176:177], v[6:7], v[24:25] op_sel_hi:[1,0,1]
	v_add_f32_dpp v28, v28, v28 quad_perm:[1,0,3,2] row_mask:0xf bank_mask:0xf
	v_add_f32_dpp v32, v32, v32 quad_perm:[1,0,3,2] row_mask:0xf bank_mask:0xf
	v_pk_fma_f32 v[26:27], v[178:179], v[6:7], v[26:27] op_sel_hi:[1,0,1]
	v_add_f32_dpp v28, v28, v28 quad_perm:[2,3,0,1] row_mask:0xf bank_mask:0xf
	v_add_f32_dpp v32, v32, v32 quad_perm:[2,3,0,1] row_mask:0xf bank_mask:0xf
	v_pk_fma_f32 v[20:21], v[84:85], v[28:29], v[20:21] op_sel_hi:[1,0,1] neg_lo:[0,1,0] neg_hi:[0,1,0]
	v_mov_b32_dpp v30, v28 row_half_mirror row_mask:0xf bank_mask:0xf
	v_pk_fma_f32 v[22:23], v[86:87], v[28:29], v[22:23] op_sel_hi:[1,0,1] neg_lo:[0,1,0] neg_hi:[0,1,0]
	v_add_f32_e32 v39, v32, v5
	v_pk_fma_f32 v[24:25], v[84:85], v[30:31], v[24:25] op_sel_hi:[1,0,1] neg_lo:[0,1,0] neg_hi:[0,1,0]
	v_pk_fma_f32 v[26:27], v[86:87], v[30:31], v[26:27] op_sel_hi:[1,0,1] neg_lo:[0,1,0] neg_hi:[0,1,0]
	ds_write_b32 v102, v39 offset:3840
	s_waitcnt lgkmcnt(1)
	v_pk_mul_f32 v[46:47], v[24:25], v[144:145] op_sel_hi:[0,1]
	v_pk_mul_f32 v[34:35], v[20:21], v[144:145] op_sel_hi:[0,1]
	v_pk_fma_f32 v[46:47], v[24:25], v[146:147], v[46:47] op_sel:[1,0,0] op_sel_hi:[1,1,1]
	v_pk_fma_f32 v[34:35], v[20:21], v[146:147], v[34:35] op_sel:[1,0,0] op_sel_hi:[1,1,1]
	v_pk_fma_f32 v[46:47], v[26:27], v[156:157], v[46:47] op_sel_hi:[0,1,1]
	v_pk_fma_f32 v[34:35], v[22:23], v[156:157], v[34:35] op_sel_hi:[0,1,1]
	v_pk_fma_f32 v[46:47], v[26:27], v[158:159], v[46:47] op_sel:[1,0,0] op_sel_hi:[1,1,1]
	v_pk_fma_f32 v[34:35], v[22:23], v[158:159], v[34:35] op_sel:[1,0,0] op_sel_hi:[1,1,1]
	v_pk_mul_f32 v[20:21], v[20:21], v[168:169]
	v_add_f32_dpp v28, v46, v34 row_half_mirror row_mask:0xf bank_mask:0xf
	v_add_f32_dpp v32, v47, v35 row_half_mirror row_mask:0xf bank_mask:0xf
	v_pk_mul_f32 v[22:23], v[22:23], v[170:171]
	v_add_f32_dpp v28, v28, v28 row_ror:8 row_mask:0xf bank_mask:0xf
	v_add_f32_dpp v32, v32, v32 row_ror:8 row_mask:0xf bank_mask:0xf
	v_pk_mul_f32 v[24:25], v[24:25], v[168:169]
	v_add_f32_dpp v28, v28, v28 quad_perm:[1,0,3,2] row_mask:0xf bank_mask:0xf
	v_add_f32_dpp v32, v32, v32 quad_perm:[1,0,3,2] row_mask:0xf bank_mask:0xf
	v_pk_mul_f32 v[26:27], v[26:27], v[170:171]
	v_add_f32_dpp v28, v28, v28 quad_perm:[2,3,0,1] row_mask:0xf bank_mask:0xf
	v_add_f32_dpp v32, v32, v32 quad_perm:[2,3,0,1] row_mask:0xf bank_mask:0xf
	v_pk_fma_f32 v[20:21], v[180:181], v[8:9], v[20:21] op_sel_hi:[1,0,1]
	v_mov_b32_dpp v30, v28 row_half_mirror row_mask:0xf bank_mask:0xf
	v_pk_fma_f32 v[22:23], v[182:183], v[8:9], v[22:23] op_sel_hi:[1,0,1]
	v_pk_fma_f32 v[24:25], v[180:181], v[10:11], v[24:25] op_sel_hi:[1,0,1]
	v_pk_fma_f32 v[26:27], v[182:183], v[10:11], v[26:27] op_sel_hi:[1,0,1]
	v_pk_fma_f32 v[20:21], v[88:89], v[28:29], v[20:21] op_sel_hi:[1,0,1] neg_lo:[0,1,0] neg_hi:[0,1,0]
	v_pk_fma_f32 v[22:23], v[90:91], v[28:29], v[22:23] op_sel_hi:[1,0,1] neg_lo:[0,1,0] neg_hi:[0,1,0]
	v_pk_fma_f32 v[24:25], v[88:89], v[30:31], v[24:25] op_sel_hi:[1,0,1] neg_lo:[0,1,0] neg_hi:[0,1,0]
	v_pk_fma_f32 v[26:27], v[90:91], v[30:31], v[26:27] op_sel_hi:[1,0,1] neg_lo:[0,1,0] neg_hi:[0,1,0]
	v_add_f32_e32 v39, v32, v9
	ds_write_b32 v102, v39 offset:3968
	s_waitcnt lgkmcnt(0)
	s_barrier
	s_add_i32 s8, s8, 1
	s_cmp_eq_u32 s8, 64
	s_cbranch_scc0 .Lrw_scan_loop
	s_setprio 0
	s_branch .LBB0_183
